# MLA tile loop on 16x16x32 bf16 MFMA (software-pipelined, hand-written) + diff-attention tile loop software-pipelined
# baseline (speedup 1.0000x reference)
; template <int DQK, int DV, int FLAGS, int qp, int kp, int vts, int op> ...
;     ...
;     bf16x8 qr[ND0];
;     { const bf16* qrow = Q + (size_t)(32 * wave + r32) * qp + 8 * hi;
; #pragma unroll
;       for (int d0 = 0; d0 < ND0; ++d0) qr[d0] = *(const bf16x8*)(qrow + 16 * d0);
; __global__ void __launch_bounds__(NTHREADS, 2) mega_fwd(Args args) {
;     ...
;             int combo, qb; causal_slot(j, 16, combo, qb);
;             const int b = combo >> 3, h = combo & 7; const size_t row0 = (size_t)b * SEQ + qb * 256;
;     ...
;             attn_unit<96, 64, AF_CAUSAL, 768, 768, SEQ, 1024>(lds, (const bf16*)(ws + A_QB) + row0 * 768 + h * 96, (const bf16*)(ws + A_KB) + (size_t)b * SEQ * 768 + h * 96,
;                                          (const bf16*)(ws + A_VTB) + ((size_t)b * 512 + h * 64) * SEQ, ATT + row0 * 1024 + 512 + h * 64, qb * 256, 0, 4 * (qb + 1), 0.f, 0.f, nullptr, 0.f, mla_skipmax);
.LBB0_526:
	s_lshr_b32 s2, s33, 3
	s_ashr_i32 s9, s33, 4
	s_lshl_b32 s16, s33, 5
	s_and_b32 s17, s2, 16
	s_bfe_u32 s2, s33, 0x40003
	s_and_b32 s10, s9, 0xffffffe0
	s_or_b32 s9, s9, 31
	s_or_b32 s3, s17, s16
	s_and_b32 s8, s33, 0x100
	s_sub_i32 s9, s9, s2
	s_or_b32 s2, s10, s2
	s_cmp_eq_u32 s8, 0
	s_cselect_b32 s2, s2, s9
	s_bfe_u32 s20, s33, 0x10002
	s_bfe_u32 s86, s3, 0x30004
	s_lshl_b32 s3, s2, 8
	s_lshl_b32 s8, s20, 14
	s_ashr_i32 s9, s3, 31
	s_add_u32 s84, s8, s3
	s_addc_u32 s85, 0, s9
	s_mul_i32 s8, s85, 0x600
	s_mul_hi_u32 s9, s84, 0x600
	s_add_i32 s9, s9, s8
	s_mul_i32 s8, s84, 0x600
	s_add_u32 s8, s81, s8
	s_addc_u32 s9, s94, s9
	s_mul_i32 s10, s86, 0xc0
	s_add_u32 s8, s8, s10
	s_addc_u32 s9, s9, 0
	s_mul_i32 s18, s20, 0x1800000
	s_add_u32 s11, s95, s18
	s_addc_u32 s13, s92, 0
	v_mov_b32_e32 v17, v212
	s_add_u32 s12, s11, s10
	s_addc_u32 s13, s13, 0
	v_readfirstlane_b32 s10, v17
	s_ashr_i32 s19, s10, 1
	v_mov_b32_e32 v0, s19
	s_movk_i32 s10, 0xffe0
	v_bfe_u32 v19, v17, 5, 1
	v_bfi_b32 v168, s10, v0, v17
	s_mov_b64 s[98:99], s[8:9]
	v_mov_b64_e32 v[2:3], s[8:9]
	v_mad_i64_i32 v[2:3], s[8:9], v168, s89, v[2:3]
	v_lshlrev_b32_e32 v0, 4, v19
	v_lshl_add_u64 v[14:15], v[2:3], 0, v[0:1]
	s_andn2_b64 vcc, exec, s[4:5]
	s_cbranch_vccnz .Lr_qorig
	v_and_b32_e32 v184, 15, v17
	v_lshrrev_b32_e32 v185, 6, v17
	v_lshl_or_b32 v184, v185, 5, v184
	v_mul_u32_u24_e32 v184, 0x600, v184
	v_bfe_u32 v185, v17, 4, 2
	v_lshl_add_u32 v184, v185, 4, v184
	v_mov_b32_e32 v185, 0
	v_lshl_add_u64 v[186:187], s[98:99], 0, v[184:185]
	global_load_dwordx4 v[2:5], v[186:187], off
	global_load_dwordx4 v[6:9], v[186:187], off offset:64
	global_load_dwordx4 v[10:13], v[186:187], off offset:128
	s_mov_b64 s[100:101], 0x6000
	v_lshl_add_u64 v[186:187], v[186:187], 0, s[100:101]
	global_load_dwordx4 v[128:131], v[186:187], off
	global_load_dwordx4 v[132:135], v[186:187], off offset:64
	global_load_dwordx4 v[136:139], v[186:187], off offset:128
	s_branch .Lr_qdone
.Lr_qorig:
	global_load_dwordx4 v[2:5], v[14:15], off
	global_load_dwordx4 v[6:9], v[14:15], off offset:32
	global_load_dwordx4 v[10:13], v[14:15], off offset:64
	global_load_dwordx4 v[128:131], v[14:15], off offset:96
	global_load_dwordx4 v[132:135], v[14:15], off offset:128
	global_load_dwordx4 v[136:139], v[14:15], off offset:160
.Lr_qdone:
	v_mul_hi_i32 v14, v17, s24
	v_lshrrev_b32_e32 v15, 31, v14
	v_ashrrev_i32_e32 v14, 1, v14
	v_add_u32_e32 v14, v14, v15
	v_mul_lo_u32 v15, v14, 12
	v_sub_u32_e32 v15, v17, v15
	v_mul_lo_u32 v16, v14, s89
	s_movk_i32 s8, 0x300
	v_lshl_add_u32 v16, v15, 4, v16
	v_cmp_gt_i32_e64 s[8:9], s8, v17
	s_and_saveexec_b64 s[10:11], s[8:9]
	s_cbranch_execz .LBB0_528
	global_load_dwordx4 v[140:143], v16, s[12:13]

; #define LAS __attribute__((address_space(3)))
; #define ATT_LSTORE(buf) do { LAS unsigned char* b_ = lds + (buf) * BUF; \
;         _Pragma("unroll") for (int i = 0; i < KPT; ++i) { if (KCH % NTHREADS == 0 || tid + i * NTHREADS < KCH) *(LAS u32x4*)(b_ + klo[i]) = kreg[i]; } \
;         _Pragma("unroll") for (int i = 0; i < VPT; ++i) *(LAS u32x4*)(b_ + vlo[i]) = vreg[i]; } while (0)
; template <int DQK, int DV, int FLAGS, int qp, int kp, int vts, int op> ...
;     ...
;     const int qpos = q0 + 32 * wave + r32, qmin_w = q0 + 32 * wave, qmax_w = qmin_w + 31;
;     f32x16 o[NDB];
; #pragma unroll
;     for (int d = 0; d < NDB; ++d)
; #pragma unroll
;         for (int r = 0; r < 16; ++r) o[d][r] = 0.f;
;     float m = (FLAGS & AF_ROBUST) ? -1e30f : 0.f, l = 0.f;
;     f32x16 negm;
; #pragma unroll
;     for (int r = 0; r < 16; ++r) negm[r] = 0.f;
;     u32x4 kreg[KPT], vreg[VPT];
;     unsigned kgo[KPT], vgo[VPT], klo[KPT], vlo[VPT];
; #pragma unroll
;     for (int i = 0; i < KPT; ++i) { const int c = tid + i * NTHREADS; const int row = c / KC, cc = c % KC; kgo[i] = (unsigned)(row * kp + cc * 8) * 2u; klo[i] = (unsigned)(row * KROW + cc * 16); }
; #pragma unroll
;     for (int i = 0; i < VPT; ++i) { const int c = tid + i * NTHREADS; const int d = c >> 3, cc = c & 7; vgo[i] = (unsigned)(d * vts + cc * 8) * 2u; vlo[i] = (unsigned)(KT_BYTES + d * VROW + cc * 16); }
;     ...
;     ATT_GLOAD((FLAGS & AF_REV) ? kt_hi - 1 : kt_lo); ATT_LSTORE(0);
;     __syncthreads();
;     ...
;             __builtin_amdgcn_sched_barrier(0);
; #pragma unroll
;             for (int c = 0; c < ND0 / 2; ++c) {
;                 if (c + 1 < ND0 / 2) {
; #pragma unroll
;                     for (int i = 0; i < 2; ++i) { kf[(c + 1) & 1][2 * i] = *(const LAS bf16x8*)(kb + (2 * c + 2 + i) * 32); kf[(c + 1) & 1][2 * i + 1] = *(const LAS bf16x8*)(kb + 32 * KROW + (2 * c + 2 + i) * 32); }
;                 }
; #pragma unroll
;                 for (int i = 0; i < 2; ++i) {
;                     p0 = __builtin_amdgcn_mfma_f32_32x32x16_bf16(kf[c & 1][2 * i], qr[2 * c + i], p0, 0, 0, 0);
;                     p1 = __builtin_amdgcn_mfma_f32_32x32x16_bf16(kf[c & 1][2 * i + 1], qr[2 * c + i], p1, 0, 0, 0);
;                 }
;                 __builtin_amdgcn_sched_barrier(0);
;             }
.LBB0_536:
	s_andn2_b64 vcc, exec, s[12:13]
	v_lshlrev_b32_e32 v170, 3, v19
	s_cbranch_vccnz .LBB0_524
	s_and_b32 s87, s19, 0xffffffe0
	s_add_i32 s16, s16, s17
	s_add_i32 s87, s87, s3
	s_lshl_b32 s15, s2, 2
	s_lshl_b32 s12, s16, 17
	s_or_b32 s88, s87, 31
	s_add_i32 s2, s15, 4
	s_bfe_u32 s17, s16, 0x30004
	s_and_b32 s12, s12, 0xe00000
	s_add_u32 s12, s14, s12
	s_addc_u32 s13, 0, 0
	s_add_u32 s12, s93, s12
	v_readlane_b32 s14, v252, 61
	v_mov_b32_e32 v21, v1
	s_addc_u32 s13, s14, s13
	s_mulk_i32 s17, 0xc0
	v_and_b32_e32 v22, 31, v17
	v_and_b32_e32 v19, 19, v17
	v_lshlrev_b32_e32 v23, 1, v17
	v_lshrrev_b32_e32 v17, 1, v17
	v_lshl_add_u64 v[176:177], s[12:13], 0, v[20:21]
	s_add_u32 s12, s18, s17
	v_and_b32_e32 v23, 8, v23
	v_and_b32_e32 v17, 4, v17
	s_addc_u32 s13, 0, 0
	v_readlane_b32 s14, v252, 63
	v_or3_b32 v17, v19, v23, v17
	s_add_u32 s12, s14, s12
	v_readlane_b32 s14, v253, 1
	v_mul_u32_u24_e32 v169, 0xd0, v17
	v_mul_u32_u24_e32 v171, 0x90, v22
	v_mov_b32_e32 v17, v1
	v_mov_b32_e32 v19, v1
	v_add_u32_e32 v22, s87, v22
	s_addc_u32 s13, s14, s13
	v_mov_b32_e32 v32, v1
	v_mov_b32_e32 v33, v1
	v_sub_u32_e32 v173, v22, v170
	v_lshl_add_u64 v[178:179], s[12:13], 0, v[16:17]
	v_lshl_add_u64 v[180:181], s[12:13], 0, v[18:19]
	v_mov_b32_e32 v34, v1
	v_mov_b32_e32 v35, v1
	v_mov_b32_e32 v36, v1
	v_mov_b32_e32 v37, v1
	v_mov_b32_e32 v38, v1
	v_mov_b32_e32 v39, v1
	v_mov_b32_e32 v40, v1
	v_mov_b32_e32 v41, v1
	v_mov_b32_e32 v42, v1
	v_mov_b32_e32 v43, v1
	v_mov_b32_e32 v44, v1
	v_mov_b32_e32 v45, v1
	v_mov_b32_e32 v46, v1
	v_mov_b32_e32 v47, v1
	v_mov_b32_e32 v183, 0
	v_mov_b64_e32 v[16:17], v[32:33]
	s_mov_b64 s[0:1], s[90:91]
	s_mov_b32 s3, 1
	s_xor_b32 s90, s15, -4
	s_mov_b64 s[82:83], 0
	s_mov_b32 s91, 63
	v_mov_b64_e32 v[18:19], v[34:35]
	v_mov_b64_e32 v[20:21], v[36:37]
	v_mov_b64_e32 v[22:23], v[38:39]
	v_mov_b64_e32 v[24:25], v[40:41]
	v_mov_b64_e32 v[26:27], v[42:43]
	v_mov_b64_e32 v[28:29], v[44:45]
	v_mov_b64_e32 v[30:31], v[46:47]
	v_mov_b32_e32 v175, 0
	v_mov_b32_e32 v48, 0
	v_mov_b32_e32 v49, v183
	v_mov_b32_e32 v50, v183
	v_mov_b32_e32 v51, v183
	v_mov_b32_e32 v52, v183
	v_mov_b32_e32 v53, v183
	v_mov_b32_e32 v54, v183
	v_mov_b32_e32 v55, v183
	v_mov_b32_e32 v56, v183
	v_mov_b32_e32 v57, v183
	v_mov_b32_e32 v58, v183
	v_mov_b32_e32 v59, v183
	v_mov_b32_e32 v60, v183
	v_mov_b32_e32 v61, v183
	v_mov_b32_e32 v62, v183
	v_mov_b32_e32 v63, v183
	s_andn2_b64 vcc, exec, s[4:5]
	s_cbranch_vccnz .Lr_fallback
	v_and_b32_e32 v59, 15, v212
	v_bfe_u32 v60, v212, 4, 2
	v_lshrrev_b32_e32 v61, 2, v59
	v_and_b32_e32 v62, 3, v59
	v_lshl_add_u32 v61, v61, 3, v62
	v_mul_u32_u24_e32 v61, 0xd0, v61
	v_lshl_add_u32 v246, v60, 4, v61
	v_mul_u32_u24_e32 v61, 0x90, v59
	v_lshl_add_u32 v247, v60, 4, v61
	v_lshlrev_b32_e32 v61, 3, v60
	v_sub_u32_e32 v61, v59, v61
	v_add_u32_e32 v248, s87, v61
	v_xor_b32_e32 v251, 0xc0, v15
	v_mov_b32_e32 v249, 0
	v_mov_b32_e32 v250, 0
	s_and_saveexec_b64 s[14:15], s[10:11]
	global_load_dwordx4 v[144:147], v[180:181], off
	s_or_b64 exec, exec, s[14:15]
	global_load_dwordx4 v[140:143], v[178:179], off
	global_load_dwordx4 v[148:151], v[176:177], off
	s_mov_b64 s[14:15], 0x80
	v_lshl_add_u64 v[176:177], v[176:177], 0, s[14:15]
	v_lshl_add_u64 v[178:179], v[178:179], 0, s[96:97]
	v_lshl_add_u64 v[180:181], v[180:181], 0, s[96:97]
	s_movk_i32 s16, 0x5800
	s_waitcnt vmcnt(0)
	v_add_u32_e32 v56, s16, v14
	v_add_u32_e32 v57, s16, v174
	v_add_u32_e32 v58, s16, v172
	ds_write_b128 v56, v[140:143]
	ds_write_b128 v57, v[148:151] offset:13312
	s_and_saveexec_b64 s[14:15], s[10:11]
	ds_write_b128 v58, v[144:147]
	s_or_b64 exec, exec, s[14:15]
	s_and_saveexec_b64 s[14:15], s[10:11]
	global_load_dwordx4 v[144:147], v[180:181], off
	s_or_b64 exec, exec, s[14:15]
	global_load_dwordx4 v[140:143], v[178:179], off
	global_load_dwordx4 v[148:151], v[176:177], off
	s_mov_b64 s[14:15], 0x80
	v_lshl_add_u64 v[176:177], v[176:177], 0, s[14:15]
	v_lshl_add_u64 v[178:179], v[178:179], 0, s[96:97]
	v_lshl_add_u64 v[180:181], v[180:181], 0, s[96:97]
	s_lshr_b32 s20, s88, 6
	s_add_i32 s20, s20, 1
	s_min_i32 s20, s20, s2
	s_mov_b32 s3, 0
	s_waitcnt lgkmcnt(0)
	s_barrier
	v_mov_b32_e32 v206, v246
	ds_read_b128 v[96:99], v206 offset:0
	ds_read_b128 v[100:103], v206 offset:832
	ds_read_b128 v[104:107], v206 offset:6656
	ds_read_b128 v[108:111], v206 offset:7488
	ds_read_b128 v[112:115], v206 offset:64
	ds_read_b128 v[116:119], v206 offset:896
	ds_read_b128 v[120:123], v206 offset:6720
	ds_read_b128 v[124:127], v206 offset:7552
	s_waitcnt lgkmcnt(0)
	v_mfma_f32_16x16x32_bf16 v[64:67], v[96:99], v[2:5], v[48:51]
	v_mfma_f32_16x16x32_bf16 v[80:83], v[96:99], v[128:131], v[52:55]
	v_mfma_f32_16x16x32_bf16 v[68:71], v[100:103], v[2:5], v[48:51]
	v_mfma_f32_16x16x32_bf16 v[84:87], v[100:103], v[128:131], v[52:55]
	v_mfma_f32_16x16x32_bf16 v[72:75], v[104:107], v[2:5], v[48:51]
	v_mfma_f32_16x16x32_bf16 v[88:91], v[104:107], v[128:131], v[52:55]
	v_mfma_f32_16x16x32_bf16 v[76:79], v[108:111], v[2:5], v[48:51]
	v_mfma_f32_16x16x32_bf16 v[92:95], v[108:111], v[128:131], v[52:55]
	v_mfma_f32_16x16x32_bf16 v[64:67], v[112:115], v[6:9], v[64:67]
	v_mfma_f32_16x16x32_bf16 v[80:83], v[112:115], v[132:135], v[80:83]
	v_mfma_f32_16x16x32_bf16 v[68:71], v[116:119], v[6:9], v[68:71]
	v_mfma_f32_16x16x32_bf16 v[84:87], v[116:119], v[132:135], v[84:87]
	v_mfma_f32_16x16x32_bf16 v[72:75], v[120:123], v[6:9], v[72:75]
	v_mfma_f32_16x16x32_bf16 v[88:91], v[120:123], v[132:135], v[88:91]
	v_mfma_f32_16x16x32_bf16 v[76:79], v[124:127], v[6:9], v[76:79]
	v_mfma_f32_16x16x32_bf16 v[92:95], v[124:127], v[132:135], v[92:95]
	ds_read_b128 v[96:99], v206 offset:128
	ds_read_b128 v[100:103], v206 offset:960
	ds_read_b128 v[104:107], v206 offset:6784
	ds_read_b128 v[108:111], v206 offset:7616
	s_waitcnt lgkmcnt(0)
	v_mfma_f32_16x16x32_bf16 v[64:67], v[96:99], v[10:13], v[64:67]
	v_mfma_f32_16x16x32_bf16 v[80:83], v[96:99], v[136:139], v[80:83]
	v_mfma_f32_16x16x32_bf16 v[68:71], v[100:103], v[10:13], v[68:71]
	v_mfma_f32_16x16x32_bf16 v[84:87], v[100:103], v[136:139], v[84:87]
	v_mfma_f32_16x16x32_bf16 v[72:75], v[104:107], v[10:13], v[72:75]
	v_mfma_f32_16x16x32_bf16 v[88:91], v[104:107], v[136:139], v[88:91]
	v_mfma_f32_16x16x32_bf16 v[76:79], v[108:111], v[10:13], v[76:79]
	v_mfma_f32_16x16x32_bf16 v[92:95], v[108:111], v[136:139], v[92:95]
; #define LAS __attribute__((address_space(3)))
; template <int DQK, int DV, int FLAGS, int qp, int kp, int vts, int op> ...
;     ...
;             __builtin_amdgcn_sched_barrier(0);
; #pragma unroll
;             for (int c = 0; c < ND0 / 2; ++c) {
;                 if (c + 1 < ND0 / 2) {
; #pragma unroll
;                     for (int i = 0; i < 2; ++i) { kf[(c + 1) & 1][2 * i] = *(const LAS bf16x8*)(kb + (2 * c + 2 + i) * 32); kf[(c + 1) & 1][2 * i + 1] = *(const LAS bf16x8*)(kb + 32 * KROW + (2 * c + 2 + i) * 32); }
;                 }
; #pragma unroll
;                 for (int i = 0; i < 2; ++i) {
;                     p0 = __builtin_amdgcn_mfma_f32_32x32x16_bf16(kf[c & 1][2 * i], qr[2 * c + i], p0, 0, 0, 0);
;                     p1 = __builtin_amdgcn_mfma_f32_32x32x16_bf16(kf[c & 1][2 * i + 1], qr[2 * c + i], p1, 0, 0, 0);
;                 }
;                 __builtin_amdgcn_sched_barrier(0);
;             }
;     ...
;             f32x2 rs2 = {0.f, 0.f};
; #pragma unroll
;             for (int r = 0; r < 16; ++r) { p0[r] = __builtin_amdgcn_exp2f(p0[r]); p1[r] = __builtin_amdgcn_exp2f(p1[r]); }
; #pragma unroll
;             for (int r = 0; r < 16; r += 2) { rs2 += (f32x2){p0[r], p0[r + 1]}; rs2 += (f32x2){p1[r], p1[r + 1]}; }
;             l += rs2.x + rs2.y;
;             bf16x8 pf[4];
;             pf[0] = pack_bf16x8(p0, 0); pf[1] = pack_bf16x8(p0, 8); pf[2] = pack_bf16x8(p1, 0); pf[3] = pack_bf16x8(p1, 8);
;             __builtin_amdgcn_sched_barrier(0);
; #pragma unroll
;             for (int d = 0; d < NDB; ++d) {
;                 if (d + 1 < NDB) {
; #pragma unroll
;                     for (int ks = 0; ks < 4; ++ks) vf[(d + 1) & 1][ks] = *(const LAS bf16x8*)(vb + (d + 1) * 32 * VROW + ks * 32);
;                 }
; #pragma unroll
;                 for (int ks = 0; ks < 4; ++ks) o[d] = __builtin_amdgcn_mfma_f32_32x32x16_bf16(vf[d & 1][ks], pf[ks], o[d], 0, 0, 0);
;                 __builtin_amdgcn_sched_barrier(0);
;             }
.Lr_top0:
	s_cmp_eq_u32 s3, 0
	s_cbranch_scc1 .Lr_gen0
	s_add_i32 s13, s3, 1
	s_cmp_ge_i32 s13, s20
	s_cbranch_scc1 .Lr_gen0
	s_add_i32 s12, s3, 1
	s_and_b32 s12, s12, 3
	s_mulk_i32 s12, 0x5800
	v_add_u32_e32 v206, s12, v246
	ds_read_b128 v[96:99], v206 offset:0
	ds_read_b128 v[100:103], v206 offset:832
	ds_read_b128 v[104:107], v206 offset:6656
	ds_read_b128 v[108:111], v206 offset:7488
	ds_read_b128 v[112:115], v206 offset:64
	ds_read_b128 v[116:119], v206 offset:896
	ds_read_b128 v[120:123], v206 offset:6720
	ds_read_b128 v[124:127], v206 offset:7552
	s_and_b32 s16, s3, 3
	s_mulk_i32 s16, 0x5800
	v_add_u32_e32 v207, s16, v247
	v_mfma_f32_16x16x32_bf16 v[32:35], v[152:155], v[214:217], v[32:35]
	v_mfma_f32_16x16x32_bf16 v[16:19], v[152:155], v[230:233], v[16:19]
	v_exp_f32_e32 v64, v64
	v_exp_f32_e32 v65, v65
	v_mfma_f32_16x16x32_bf16 v[36:39], v[156:159], v[214:217], v[36:39]
	v_mfma_f32_16x16x32_bf16 v[20:23], v[156:159], v[230:233], v[20:23]
	v_exp_f32_e32 v80, v80
	v_exp_f32_e32 v81, v81
	v_pk_add_f32 v[204:205], v[64:65], 0 op_sel_hi:[1,0]
	v_mfma_f32_16x16x32_bf16 v[40:43], v[160:163], v[214:217], v[40:43]
	v_mfma_f32_16x16x32_bf16 v[24:27], v[160:163], v[230:233], v[24:27]
	v_exp_f32_e32 v66, v66
	v_exp_f32_e32 v67, v67
	v_pk_add_f32 v[208:209], v[80:81], 0 op_sel_hi:[1,0]
	v_mfma_f32_16x16x32_bf16 v[44:47], v[164:167], v[214:217], v[44:47]
	v_mfma_f32_16x16x32_bf16 v[28:31], v[164:167], v[230:233], v[28:31]
	v_exp_f32_e32 v82, v82
	v_exp_f32_e32 v83, v83
	v_pk_add_f32 v[204:205], v[66:67], v[204:205]
	ds_read_b128 v[152:155], v207 offset:13312
	ds_read_b128 v[156:159], v207 offset:15616
	ds_read_b128 v[160:163], v207 offset:17920
	ds_read_b128 v[164:167], v207 offset:20224
	v_mfma_f32_16x16x32_bf16 v[32:35], v[188:191], v[218:221], v[32:35]
	v_mfma_f32_16x16x32_bf16 v[16:19], v[188:191], v[234:237], v[16:19]
	v_exp_f32_e32 v68, v68
	v_exp_f32_e32 v69, v69
	v_pk_add_f32 v[208:209], v[82:83], v[208:209]
	v_mfma_f32_16x16x32_bf16 v[36:39], v[192:195], v[218:221], v[36:39]
	v_mfma_f32_16x16x32_bf16 v[20:23], v[192:195], v[234:237], v[20:23]
	v_exp_f32_e32 v84, v84
	v_exp_f32_e32 v85, v85
	v_pk_add_f32 v[204:205], v[68:69], v[204:205]
	v_mfma_f32_16x16x32_bf16 v[40:43], v[196:199], v[218:221], v[40:43]
	v_mfma_f32_16x16x32_bf16 v[24:27], v[196:199], v[234:237], v[24:27]
	v_exp_f32_e32 v70, v70
	v_exp_f32_e32 v71, v71
	v_pk_add_f32 v[208:209], v[84:85], v[208:209]
	v_mfma_f32_16x16x32_bf16 v[44:47], v[200:203], v[218:221], v[44:47]
	v_mfma_f32_16x16x32_bf16 v[28:31], v[200:203], v[234:237], v[28:31]
	v_exp_f32_e32 v86, v86
	v_exp_f32_e32 v87, v87
	v_pk_add_f32 v[204:205], v[70:71], v[204:205]
	s_waitcnt lgkmcnt(8)
	v_mfma_f32_16x16x32_bf16 v[214:217], v[96:99], v[2:5], v[48:51]
	v_mfma_f32_16x16x32_bf16 v[230:233], v[96:99], v[128:131], v[52:55]
	v_exp_f32_e32 v72, v72
	v_exp_f32_e32 v73, v73
	v_pk_add_f32 v[208:209], v[86:87], v[208:209]
	v_mfma_f32_16x16x32_bf16 v[218:221], v[100:103], v[2:5], v[48:51]
	v_mfma_f32_16x16x32_bf16 v[234:237], v[100:103], v[128:131], v[52:55]
	v_exp_f32_e32 v88, v88
	v_exp_f32_e32 v89, v89
	v_pk_add_f32 v[204:205], v[72:73], v[204:205]
	v_mfma_f32_16x16x32_bf16 v[222:225], v[104:107], v[2:5], v[48:51]
	v_mfma_f32_16x16x32_bf16 v[238:241], v[104:107], v[128:131], v[52:55]
	v_exp_f32_e32 v74, v74
	v_exp_f32_e32 v75, v75
	v_pk_add_f32 v[208:209], v[88:89], v[208:209]
	v_mfma_f32_16x16x32_bf16 v[226:229], v[108:111], v[2:5], v[48:51]
	v_mfma_f32_16x16x32_bf16 v[242:245], v[108:111], v[128:131], v[52:55]
	v_exp_f32_e32 v90, v90
	v_exp_f32_e32 v91, v91
	v_pk_add_f32 v[204:205], v[74:75], v[204:205]
	ds_read_b128 v[96:99], v206 offset:128
	ds_read_b128 v[100:103], v206 offset:960
	ds_read_b128 v[104:107], v206 offset:6784
	ds_read_b128 v[108:111], v206 offset:7616
	s_waitcnt lgkmcnt(8)
	v_mfma_f32_16x16x32_bf16 v[214:217], v[112:115], v[6:9], v[214:217]
	v_mfma_f32_16x16x32_bf16 v[230:233], v[112:115], v[132:135], v[230:233]
	v_exp_f32_e32 v76, v76
	v_exp_f32_e32 v77, v77
	v_pk_add_f32 v[208:209], v[90:91], v[208:209]
	v_mfma_f32_16x16x32_bf16 v[218:221], v[116:119], v[6:9], v[218:221]
	v_mfma_f32_16x16x32_bf16 v[234:237], v[116:119], v[132:135], v[234:237]
	v_exp_f32_e32 v92, v92
	v_exp_f32_e32 v93, v93
	v_pk_add_f32 v[204:205], v[76:77], v[204:205]
	v_mfma_f32_16x16x32_bf16 v[222:225], v[120:123], v[6:9], v[222:225]
	v_mfma_f32_16x16x32_bf16 v[238:241], v[120:123], v[132:135], v[238:241]
	v_exp_f32_e32 v78, v78
	v_exp_f32_e32 v79, v79
	v_pk_add_f32 v[208:209], v[92:93], v[208:209]
	v_mfma_f32_16x16x32_bf16 v[226:229], v[124:127], v[6:9], v[226:229]
	v_mfma_f32_16x16x32_bf16 v[242:245], v[124:127], v[132:135], v[242:245]
	v_exp_f32_e32 v94, v94
	v_exp_f32_e32 v95, v95
	v_pk_add_f32 v[204:205], v[78:79], v[204:205]
	ds_read_b128 v[188:191], v207 offset:13376
	ds_read_b128 v[192:195], v207 offset:15680
	ds_read_b128 v[196:199], v207 offset:17984
	ds_read_b128 v[200:203], v207 offset:20288
	s_waitcnt lgkmcnt(4)
	v_mfma_f32_16x16x32_bf16 v[214:217], v[96:99], v[10:13], v[214:217]
	v_mfma_f32_16x16x32_bf16 v[230:233], v[96:99], v[136:139], v[230:233]
	s_nop 0
	v_pk_add_f32 v[208:209], v[94:95], v[208:209]
	v_cvt_pk_bf16_f32 v64, v64, v65
	v_cvt_pk_bf16_f32 v65, v66, v67
	v_cvt_pk_bf16_f32 v66, v68, v69
	v_cvt_pk_bf16_f32 v67, v70, v71
	v_mfma_f32_16x16x32_bf16 v[218:221], v[100:103], v[10:13], v[218:221]
	v_mfma_f32_16x16x32_bf16 v[234:237], v[100:103], v[136:139], v[234:237]
	v_cvt_pk_bf16_f32 v68, v72, v73
	v_cvt_pk_bf16_f32 v69, v74, v75
	v_cvt_pk_bf16_f32 v70, v76, v77
	v_cvt_pk_bf16_f32 v71, v78, v79
	v_cvt_pk_bf16_f32 v80, v80, v81
	v_cvt_pk_bf16_f32 v81, v82, v83
	v_mfma_f32_16x16x32_bf16 v[222:225], v[104:107], v[10:13], v[222:225]
	v_mfma_f32_16x16x32_bf16 v[238:241], v[104:107], v[136:139], v[238:241]
	v_cvt_pk_bf16_f32 v82, v84, v85
	v_cvt_pk_bf16_f32 v83, v86, v87
	v_cvt_pk_bf16_f32 v84, v88, v89
	v_cvt_pk_bf16_f32 v85, v90, v91
	v_cvt_pk_bf16_f32 v86, v92, v93
	v_cvt_pk_bf16_f32 v87, v94, v95
	v_mfma_f32_16x16x32_bf16 v[226:229], v[108:111], v[10:13], v[226:229]
	v_mfma_f32_16x16x32_bf16 v[242:245], v[108:111], v[136:139], v[242:245]
	v_add_f32_e32 v210, v204, v205
	v_add_f32_e32 v211, v208, v209
	v_add_f32_e32 v175, v175, v210
	v_add_f32_e32 v249, v249, v211
	s_branch .Lr_tail0
; #define LAS __attribute__((address_space(3)))
; template <int DQK, int DV, int FLAGS, int qp, int kp, int vts, int op> ...
;     ...
;             bf16x8 vf[2][4];
; #pragma unroll
;             for (int ks = 0; ks < 4; ++ks) vf[0][ks] = *(const LAS bf16x8*)(vb + ks * 32);
;             __builtin_amdgcn_sched_barrier(0);
;             bool need_mask = false;
;             if (FLAGS & AF_CAUSAL) need_mask = need_mask || (kv0 + 63 > qmin_w);
;             if (FLAGS & AF_WINDOW) need_mask = need_mask || (kv0 < qmax_w - (SWA_W - 1));
;             if (need_mask) {
; #pragma unroll
;                 for (int r = 0; r < 16; ++r) { const int c = 16 * (r >> 3) + (r & 7);
;                     bool m0 = false, m1 = false;
;                     if (FLAGS & AF_CAUSAL) { m0 = m0 || (c > nrel); m1 = m1 || (c + 32 > nrel); }
;                     if (FLAGS & AF_WINDOW) { m0 = m0 || (c <= nrel - SWA_W); m1 = m1 || (c + 32 <= nrel - SWA_W); }
;                     if (m0) p0[r] = -INFINITY; if (m1) p1[r] = -INFINITY; }
;             }
;     ...
;             __builtin_amdgcn_sched_barrier(0);
; #pragma unroll
;             for (int d = 0; d < NDB; ++d) {
;                 if (d + 1 < NDB) {
; #pragma unroll
;                     for (int ks = 0; ks < 4; ++ks) vf[(d + 1) & 1][ks] = *(const LAS bf16x8*)(vb + (d + 1) * 32 * VROW + ks * 32);
;                 }
; #pragma unroll
;                 for (int ks = 0; ks < 4; ++ks) o[d] = __builtin_amdgcn_mfma_f32_32x32x16_bf16(vf[d & 1][ks], pf[ks], o[d], 0, 0, 0);
;                 __builtin_amdgcn_sched_barrier(0);
;             }
.Lr_gen0:
	s_add_i32 s13, s3, 1
	s_cmp_ge_i32 s13, s20
	s_cbranch_scc1 .Lr_nokr_p0
	s_add_i32 s12, s3, 1
	s_and_b32 s12, s12, 3
	s_mulk_i32 s12, 0x5800
	v_add_u32_e32 v206, s12, v246
	ds_read_b128 v[96:99], v206 offset:0
	ds_read_b128 v[100:103], v206 offset:832
	ds_read_b128 v[104:107], v206 offset:6656
	ds_read_b128 v[108:111], v206 offset:7488
	ds_read_b128 v[112:115], v206 offset:64
	ds_read_b128 v[116:119], v206 offset:896
	ds_read_b128 v[120:123], v206 offset:6720
	ds_read_b128 v[124:127], v206 offset:7552
.Lr_nokr_p0:
	s_cmp_eq_u32 s3, 0
	s_cbranch_scc1 .Lr_nopv_p0
	s_cmp_gt_i32 s3, s20
	s_cbranch_scc1 .Lr_nopv_p0
	s_waitcnt lgkmcnt(8)
	v_mfma_f32_16x16x32_bf16 v[32:35], v[152:155], v[214:217], v[32:35]
	v_mfma_f32_16x16x32_bf16 v[16:19], v[152:155], v[230:233], v[16:19]
	v_mfma_f32_16x16x32_bf16 v[36:39], v[156:159], v[214:217], v[36:39]
	v_mfma_f32_16x16x32_bf16 v[20:23], v[156:159], v[230:233], v[20:23]
	v_mfma_f32_16x16x32_bf16 v[40:43], v[160:163], v[214:217], v[40:43]
	v_mfma_f32_16x16x32_bf16 v[24:27], v[160:163], v[230:233], v[24:27]
	v_mfma_f32_16x16x32_bf16 v[44:47], v[164:167], v[214:217], v[44:47]
	v_mfma_f32_16x16x32_bf16 v[28:31], v[164:167], v[230:233], v[28:31]
	v_mfma_f32_16x16x32_bf16 v[32:35], v[188:191], v[218:221], v[32:35]
	v_mfma_f32_16x16x32_bf16 v[16:19], v[188:191], v[234:237], v[16:19]
	v_mfma_f32_16x16x32_bf16 v[36:39], v[192:195], v[218:221], v[36:39]
	v_mfma_f32_16x16x32_bf16 v[20:23], v[192:195], v[234:237], v[20:23]
	v_mfma_f32_16x16x32_bf16 v[40:43], v[196:199], v[218:221], v[40:43]
	v_mfma_f32_16x16x32_bf16 v[24:27], v[196:199], v[234:237], v[24:27]
	v_mfma_f32_16x16x32_bf16 v[44:47], v[200:203], v[218:221], v[44:47]
	v_mfma_f32_16x16x32_bf16 v[28:31], v[200:203], v[234:237], v[28:31]
.Lr_nopv_p0:
	s_cmp_ge_i32 s3, s20
	s_cbranch_scc1 .Lr_nosm_p0
	s_and_b32 s16, s3, 3
	s_mulk_i32 s16, 0x5800
	v_add_u32_e32 v207, s16, v247
	ds_read_b128 v[152:155], v207 offset:13312
	ds_read_b128 v[156:159], v207 offset:15616
	ds_read_b128 v[160:163], v207 offset:17920
	ds_read_b128 v[164:167], v207 offset:20224
	ds_read_b128 v[188:191], v207 offset:13376
	ds_read_b128 v[192:195], v207 offset:15680
	ds_read_b128 v[196:199], v207 offset:17984
	ds_read_b128 v[200:203], v207 offset:20288
	s_nop 7
	s_nop 7
	s_add_i32 s12, s3, 1
	s_cmp_lg_u32 s12, s20
	s_cbranch_scc1 .Lr_nomask_p0
	s_lshl_b32 s12, s3, 6
	v_subrev_u32_e32 v210, s12, v248
	v_add_u32_e32 v211, 16, v210
	v_cmp_gt_i32_e64 s[40:41], 0, v210
	v_cmp_gt_i32_e64 s[42:43], 1, v210
	v_cmp_gt_i32_e64 s[44:45], 2, v210
	v_cmp_gt_i32_e64 s[46:47], 3, v210
	v_cndmask_b32_e64 v64, v64, v182, s[40:41]
	v_cmp_gt_i32_e64 s[40:41], 4, v210
	v_cndmask_b32_e64 v65, v65, v182, s[42:43]
	v_cmp_gt_i32_e64 s[42:43], 5, v210
	v_cndmask_b32_e64 v66, v66, v182, s[44:45]
	v_cmp_gt_i32_e64 s[44:45], 6, v210
	v_cndmask_b32_e64 v67, v67, v182, s[46:47]
	v_cmp_gt_i32_e64 s[46:47], 7, v210
	v_cndmask_b32_e64 v68, v68, v182, s[40:41]
	v_cmp_gt_i32_e64 s[40:41], 32, v210
	v_cndmask_b32_e64 v69, v69, v182, s[42:43]
	v_cmp_gt_i32_e64 s[42:43], 33, v210
	v_cndmask_b32_e64 v70, v70, v182, s[44:45]
	v_cmp_gt_i32_e64 s[44:45], 34, v210
	v_cndmask_b32_e64 v71, v71, v182, s[46:47]
	v_cmp_gt_i32_e64 s[46:47], 35, v210
	v_cndmask_b32_e64 v72, v72, v182, s[40:41]
	v_cmp_gt_i32_e64 s[40:41], 36, v210
	v_cndmask_b32_e64 v73, v73, v182, s[42:43]
	v_cmp_gt_i32_e64 s[42:43], 37, v210
	v_cndmask_b32_e64 v74, v74, v182, s[44:45]
	v_cmp_gt_i32_e64 s[44:45], 38, v210
	v_cndmask_b32_e64 v75, v75, v182, s[46:47]
	v_cmp_gt_i32_e64 s[46:47], 39, v210
	v_cndmask_b32_e64 v76, v76, v182, s[40:41]
	v_cmp_gt_i32_e64 s[40:41], 0, v211
	v_cndmask_b32_e64 v77, v77, v182, s[42:43]
	v_cmp_gt_i32_e64 s[42:43], 1, v211
	v_cndmask_b32_e64 v78, v78, v182, s[44:45]
	v_cmp_gt_i32_e64 s[44:45], 2, v211
	v_cndmask_b32_e64 v79, v79, v182, s[46:47]
	v_cmp_gt_i32_e64 s[46:47], 3, v211
	v_cndmask_b32_e64 v80, v80, v182, s[40:41]
	v_cmp_gt_i32_e64 s[40:41], 4, v211
	v_cndmask_b32_e64 v81, v81, v182, s[42:43]
	v_cmp_gt_i32_e64 s[42:43], 5, v211
	v_cndmask_b32_e64 v82, v82, v182, s[44:45]
	v_cmp_gt_i32_e64 s[44:45], 6, v211
	v_cndmask_b32_e64 v83, v83, v182, s[46:47]
	v_cmp_gt_i32_e64 s[46:47], 7, v211
	v_cndmask_b32_e64 v84, v84, v182, s[40:41]
	v_cmp_gt_i32_e64 s[40:41], 32, v211
	v_cndmask_b32_e64 v85, v85, v182, s[42:43]
	v_cmp_gt_i32_e64 s[42:43], 33, v211
	v_cndmask_b32_e64 v86, v86, v182, s[44:45]
	v_cmp_gt_i32_e64 s[44:45], 34, v211
	v_cndmask_b32_e64 v87, v87, v182, s[46:47]
	v_cmp_gt_i32_e64 s[46:47], 35, v211
	v_cndmask_b32_e64 v88, v88, v182, s[40:41]
	v_cmp_gt_i32_e64 s[40:41], 36, v211
	v_cndmask_b32_e64 v89, v89, v182, s[42:43]
	v_cmp_gt_i32_e64 s[42:43], 37, v211
	v_cndmask_b32_e64 v90, v90, v182, s[44:45]
	v_cmp_gt_i32_e64 s[44:45], 38, v211
	v_cndmask_b32_e64 v91, v91, v182, s[46:47]
	v_cmp_gt_i32_e64 s[46:47], 39, v211
	v_cndmask_b32_e64 v92, v92, v182, s[40:41]
	v_cndmask_b32_e64 v93, v93, v182, s[42:43]
	v_cndmask_b32_e64 v94, v94, v182, s[44:45]
	v_cndmask_b32_e64 v95, v95, v182, s[46:47]
; #define MX3(a, b, c) __builtin_fmaxf(__builtin_fmaxf((a), (b)), (c))
; template <int DQK, int DV, int FLAGS, int qp, int kp, int vts, int op> ...
;     ...
;             float mx = 0.f;
;             if ((FLAGS & AF_ROBUST) || !started || !skipmax) {
;               float a = MX3(p0[0], p0[1], p1[0]), b = MX3(p0[2], p0[3], p1[1]); a = MX3(a, p1[2], p1[3]);
; #pragma unroll
;               for (int r = 4; r < 16; r += 4) { a = MX3(a, p0[r], p0[r + 1]); b = MX3(b, p0[r + 2], p0[r + 3]); a = MX3(a, p1[r], p1[r + 1]); b = MX3(b, p1[r + 2], p1[r + 3]); }
;               mx = __builtin_fmaxf(a, b);
;               if ((FLAGS & AF_ROBUST) || !started) mx = __builtin_fmaxf(mx, shfl_xor_l(mx, 32, lane)); }
;             if (FLAGS & AF_ROBUST) {
;                 if (__any(mx > m + 8.0f)) {
;                     const float mn = fmaxf(m, mx), alpha = __builtin_amdgcn_exp2f(m - mn);
;                     l *= alpha; m = mn;
; #pragma unroll
;                     for (int d = 0; d < NDB; ++d)
; #pragma unroll
;                         for (int r = 0; r < 16; ++r) o[d][r] *= alpha;
;                 }
; #pragma unroll
;                 for (int r = 0; r < 16; ++r) { p0[r] -= m; p1[r] -= m; }
;             } else {
;                 if (!started) {
;                     started = true;
;                     m = mx;
; #pragma unroll
;                     for (int r = 0; r < 16; ++r) { p0[r] -= mx; p1[r] -= mx; }
;                     if (!(FLAGS & AF_ALIBI)) {
; #pragma unroll
;                         for (int r = 0; r < 16; ++r) negm[r] = -m;
;                     }
;                 } else if (!skipmax && __any(mx > 64.0f)) {
;                     mx = __builtin_fmaxf(mx, shfl_xor_l(mx, 32, lane));
;                     const float dl = __builtin_fmaxf(mx, 0.f), alpha = __builtin_amdgcn_exp2f(-dl);
;                     m += dl; l *= alpha;
; #pragma unroll
;                     for (int r = 0; r < 16; ++r) { p0[r] -= dl; p1[r] -= dl; }
; #pragma unroll
;                     for (int d = 0; d < NDB; ++d)
; #pragma unroll
;                         for (int r = 0; r < 16; ++r) o[d][r] *= alpha;
;                     if (!(FLAGS & AF_ALIBI)) {
; #pragma unroll
;                         for (int r = 0; r < 16; ++r) negm[r] = -m;
;                     }
;                 }
;             }
;             f32x2 rs2 = {0.f, 0.f};
; #pragma unroll
.Lr_nomask_p0:
	s_cmp_lg_u32 s3, 0
	s_cbranch_scc1 .Lr_notfirst_p0
	v_max3_f32 v59, v64, v65, v66
	v_max3_f32 v60, v80, v81, v82
	v_max3_f32 v59, v59, v67, v68
	v_max3_f32 v60, v60, v83, v84
	v_max3_f32 v59, v59, v69, v70
	v_max3_f32 v60, v60, v85, v86
	v_max3_f32 v59, v59, v71, v72
	v_max3_f32 v60, v60, v87, v88
	v_max3_f32 v59, v59, v73, v74
	v_max3_f32 v60, v60, v89, v90
	v_max3_f32 v59, v59, v75, v76
	v_max3_f32 v60, v60, v91, v92
	v_max3_f32 v59, v59, v77, v78
	v_max3_f32 v60, v60, v93, v94
	v_max_f32_e32 v59, v59, v79
	v_max_f32_e32 v60, v60, v95
	s_nop 1
	ds_bpermute_b32 v61, v251, v59
	ds_bpermute_b32 v62, v251, v60
	s_waitcnt lgkmcnt(0)
	v_max_f32_e32 v59, v59, v61
	v_max_f32_e32 v60, v60, v62
	s_nop 1
	ds_bpermute_b32 v61, v15, v59
	ds_bpermute_b32 v62, v15, v60
	s_waitcnt lgkmcnt(0)
	v_max_f32_e32 v183, v59, v61
	v_max_f32_e32 v250, v60, v62
	v_sub_f32_e32 v64, v64, v183
	v_sub_f32_e32 v80, v80, v250
	v_sub_f32_e32 v65, v65, v183
	v_sub_f32_e32 v81, v81, v250
	v_sub_f32_e32 v66, v66, v183
	v_sub_f32_e32 v82, v82, v250
	v_sub_f32_e32 v67, v67, v183
	v_sub_f32_e32 v83, v83, v250
	v_sub_f32_e32 v68, v68, v183
	v_sub_f32_e32 v84, v84, v250
	v_sub_f32_e32 v69, v69, v183
	v_sub_f32_e32 v85, v85, v250
	v_sub_f32_e32 v70, v70, v183
	v_sub_f32_e32 v86, v86, v250
	v_sub_f32_e32 v71, v71, v183
	v_sub_f32_e32 v87, v87, v250
	v_sub_f32_e32 v72, v72, v183
	v_sub_f32_e32 v88, v88, v250
	v_sub_f32_e32 v73, v73, v183
	v_sub_f32_e32 v89, v89, v250
	v_sub_f32_e32 v74, v74, v183
	v_sub_f32_e32 v90, v90, v250
	v_sub_f32_e32 v75, v75, v183
	v_sub_f32_e32 v91, v91, v250
	v_sub_f32_e32 v76, v76, v183
	v_sub_f32_e32 v92, v92, v250
	v_sub_f32_e32 v77, v77, v183
	v_sub_f32_e32 v93, v93, v250
	v_sub_f32_e32 v78, v78, v183
	v_sub_f32_e32 v94, v94, v250
	v_sub_f32_e32 v79, v79, v183
	v_sub_f32_e32 v95, v95, v250
	v_xor_b32_e32 v48, 0x80000000, v183
	v_xor_b32_e32 v52, 0x80000000, v250
	v_mov_b32_e32 v49, v48
	v_mov_b32_e32 v53, v52
	v_mov_b32_e32 v50, v48
	v_mov_b32_e32 v54, v52
	v_mov_b32_e32 v51, v48
	v_mov_b32_e32 v55, v52
.Lr_notfirst_p0:
	v_exp_f32_e32 v64, v64
	v_exp_f32_e32 v65, v65
	v_exp_f32_e32 v80, v80
	v_exp_f32_e32 v81, v81
	v_pk_add_f32 v[204:205], v[64:65], 0 op_sel_hi:[1,0]
	v_exp_f32_e32 v66, v66
	v_exp_f32_e32 v67, v67
	v_pk_add_f32 v[208:209], v[80:81], 0 op_sel_hi:[1,0]
	v_exp_f32_e32 v82, v82
	v_exp_f32_e32 v83, v83
	v_pk_add_f32 v[204:205], v[66:67], v[204:205]
	v_exp_f32_e32 v68, v68
	v_exp_f32_e32 v69, v69
	v_pk_add_f32 v[208:209], v[82:83], v[208:209]
	v_exp_f32_e32 v84, v84
	v_exp_f32_e32 v85, v85
	v_pk_add_f32 v[204:205], v[68:69], v[204:205]
	v_exp_f32_e32 v70, v70
	v_exp_f32_e32 v71, v71
	v_pk_add_f32 v[208:209], v[84:85], v[208:209]
	v_exp_f32_e32 v86, v86
	v_exp_f32_e32 v87, v87
	v_pk_add_f32 v[204:205], v[70:71], v[204:205]
	v_exp_f32_e32 v72, v72
	v_exp_f32_e32 v73, v73
	v_pk_add_f32 v[208:209], v[86:87], v[208:209]
	v_exp_f32_e32 v88, v88
	v_exp_f32_e32 v89, v89
	v_pk_add_f32 v[204:205], v[72:73], v[204:205]
	v_exp_f32_e32 v74, v74
	v_exp_f32_e32 v75, v75
	v_pk_add_f32 v[208:209], v[88:89], v[208:209]
	v_exp_f32_e32 v90, v90
	v_exp_f32_e32 v91, v91
	v_pk_add_f32 v[204:205], v[74:75], v[204:205]
	v_exp_f32_e32 v76, v76
	v_exp_f32_e32 v77, v77
	v_pk_add_f32 v[208:209], v[90:91], v[208:209]
	v_exp_f32_e32 v92, v92
	v_exp_f32_e32 v93, v93
	v_pk_add_f32 v[204:205], v[76:77], v[204:205]
	v_exp_f32_e32 v78, v78
	v_exp_f32_e32 v79, v79
	v_pk_add_f32 v[208:209], v[92:93], v[208:209]
	v_exp_f32_e32 v94, v94
	v_exp_f32_e32 v95, v95
	v_pk_add_f32 v[204:205], v[78:79], v[204:205]
	s_nop 0
	v_pk_add_f32 v[208:209], v[94:95], v[208:209]
	v_cvt_pk_bf16_f32 v64, v64, v65
	v_cvt_pk_bf16_f32 v65, v66, v67
	v_cvt_pk_bf16_f32 v66, v68, v69
	v_cvt_pk_bf16_f32 v67, v70, v71
	v_cvt_pk_bf16_f32 v68, v72, v73
	v_cvt_pk_bf16_f32 v69, v74, v75
	v_cvt_pk_bf16_f32 v70, v76, v77
	v_cvt_pk_bf16_f32 v71, v78, v79
	v_cvt_pk_bf16_f32 v80, v80, v81
	v_cvt_pk_bf16_f32 v81, v82, v83
	v_cvt_pk_bf16_f32 v82, v84, v85
	v_cvt_pk_bf16_f32 v83, v86, v87
	v_cvt_pk_bf16_f32 v84, v88, v89
	v_cvt_pk_bf16_f32 v85, v90, v91
	v_cvt_pk_bf16_f32 v86, v92, v93
	v_cvt_pk_bf16_f32 v87, v94, v95
	v_add_f32_e32 v210, v204, v205
	v_add_f32_e32 v211, v208, v209
	v_add_f32_e32 v175, v175, v210
	v_add_f32_e32 v249, v249, v211
; #define LAS __attribute__((address_space(3)))
; template <int DQK, int DV, int FLAGS, int qp, int kp, int vts, int op> ...
;     ...
;             __builtin_amdgcn_sched_barrier(0);
; #pragma unroll
;             for (int c = 0; c < ND0 / 2; ++c) {
;                 if (c + 1 < ND0 / 2) {
; #pragma unroll
;                     for (int i = 0; i < 2; ++i) { kf[(c + 1) & 1][2 * i] = *(const LAS bf16x8*)(kb + (2 * c + 2 + i) * 32); kf[(c + 1) & 1][2 * i + 1] = *(const LAS bf16x8*)(kb + 32 * KROW + (2 * c + 2 + i) * 32); }
;                 }
; #pragma unroll
;                 for (int i = 0; i < 2; ++i) {
;                     p0 = __builtin_amdgcn_mfma_f32_32x32x16_bf16(kf[c & 1][2 * i], qr[2 * c + i], p0, 0, 0, 0);
;                     p1 = __builtin_amdgcn_mfma_f32_32x32x16_bf16(kf[c & 1][2 * i + 1], qr[2 * c + i], p1, 0, 0, 0);
;                 }
;                 __builtin_amdgcn_sched_barrier(0);
;             }
.Lr_nosm_p0:
	s_cmp_ge_i32 s13, s20
	s_cbranch_scc1 .Lr_noqk_p0
	s_waitcnt lgkmcnt(0)
	v_mfma_f32_16x16x32_bf16 v[214:217], v[96:99], v[2:5], v[48:51]
	v_mfma_f32_16x16x32_bf16 v[230:233], v[96:99], v[128:131], v[52:55]
	v_mfma_f32_16x16x32_bf16 v[218:221], v[100:103], v[2:5], v[48:51]
	v_mfma_f32_16x16x32_bf16 v[234:237], v[100:103], v[128:131], v[52:55]
	v_mfma_f32_16x16x32_bf16 v[222:225], v[104:107], v[2:5], v[48:51]
	v_mfma_f32_16x16x32_bf16 v[238:241], v[104:107], v[128:131], v[52:55]
	v_mfma_f32_16x16x32_bf16 v[226:229], v[108:111], v[2:5], v[48:51]
	v_mfma_f32_16x16x32_bf16 v[242:245], v[108:111], v[128:131], v[52:55]
	v_mfma_f32_16x16x32_bf16 v[214:217], v[112:115], v[6:9], v[214:217]
	v_mfma_f32_16x16x32_bf16 v[230:233], v[112:115], v[132:135], v[230:233]
	v_mfma_f32_16x16x32_bf16 v[218:221], v[116:119], v[6:9], v[218:221]
	v_mfma_f32_16x16x32_bf16 v[234:237], v[116:119], v[132:135], v[234:237]
	v_mfma_f32_16x16x32_bf16 v[222:225], v[120:123], v[6:9], v[222:225]
	v_mfma_f32_16x16x32_bf16 v[238:241], v[120:123], v[132:135], v[238:241]
	v_mfma_f32_16x16x32_bf16 v[226:229], v[124:127], v[6:9], v[226:229]
	v_mfma_f32_16x16x32_bf16 v[242:245], v[124:127], v[132:135], v[242:245]
	ds_read_b128 v[96:99], v206 offset:128
	ds_read_b128 v[100:103], v206 offset:960
	ds_read_b128 v[104:107], v206 offset:6784
	ds_read_b128 v[108:111], v206 offset:7616
	s_waitcnt lgkmcnt(0)
	v_mfma_f32_16x16x32_bf16 v[214:217], v[96:99], v[10:13], v[214:217]
	v_mfma_f32_16x16x32_bf16 v[230:233], v[96:99], v[136:139], v[230:233]
	v_mfma_f32_16x16x32_bf16 v[218:221], v[100:103], v[10:13], v[218:221]
	v_mfma_f32_16x16x32_bf16 v[234:237], v[100:103], v[136:139], v[234:237]
	v_mfma_f32_16x16x32_bf16 v[222:225], v[104:107], v[10:13], v[222:225]
	v_mfma_f32_16x16x32_bf16 v[238:241], v[104:107], v[136:139], v[238:241]
	v_mfma_f32_16x16x32_bf16 v[226:229], v[108:111], v[10:13], v[226:229]
	v_mfma_f32_16x16x32_bf16 v[242:245], v[108:111], v[136:139], v[242:245]
.Lr_noqk_p0:
.Lr_tail0:
	s_add_i32 s12, s3, 2
	s_cmp_ge_i32 s12, s2
	s_cbranch_scc1 .Lr_nols_p0
	s_and_b32 s16, s12, 3
	s_mulk_i32 s16, 0x5800
	s_waitcnt vmcnt(0)
	v_add_u32_e32 v56, s16, v14
	v_add_u32_e32 v57, s16, v174
	v_add_u32_e32 v58, s16, v172
	ds_write_b128 v56, v[140:143]
	ds_write_b128 v57, v[148:151] offset:13312
	s_and_saveexec_b64 s[14:15], s[10:11]
	ds_write_b128 v58, v[144:147]
	s_or_b64 exec, exec, s[14:15]
	s_add_i32 s12, s3, 3
	s_cmp_ge_i32 s12, s2
	s_cbranch_scc1 .Lr_nols_p0
	s_and_saveexec_b64 s[14:15], s[10:11]
	global_load_dwordx4 v[144:147], v[180:181], off
	s_or_b64 exec, exec, s[14:15]
	global_load_dwordx4 v[140:143], v[178:179], off
	global_load_dwordx4 v[148:151], v[176:177], off
	s_mov_b64 s[14:15], 0x80
	v_lshl_add_u64 v[176:177], v[176:177], 0, s[14:15]
	v_lshl_add_u64 v[178:179], v[178:179], 0, s[96:97]
	v_lshl_add_u64 v[180:181], v[180:181], 0, s[96:97]

; #define LAS __attribute__((address_space(3)))
; template <int DQK, int DV, int FLAGS, int qp, int kp, int vts, int op> ...
;     ...
;             __builtin_amdgcn_sched_barrier(0);
; #pragma unroll
;             for (int c = 0; c < ND0 / 2; ++c) {
;                 if (c + 1 < ND0 / 2) {
; #pragma unroll
;                     for (int i = 0; i < 2; ++i) { kf[(c + 1) & 1][2 * i] = *(const LAS bf16x8*)(kb + (2 * c + 2 + i) * 32); kf[(c + 1) & 1][2 * i + 1] = *(const LAS bf16x8*)(kb + 32 * KROW + (2 * c + 2 + i) * 32); }
;                 }
; #pragma unroll
;                 for (int i = 0; i < 2; ++i) {
;                     p0 = __builtin_amdgcn_mfma_f32_32x32x16_bf16(kf[c & 1][2 * i], qr[2 * c + i], p0, 0, 0, 0);
;                     p1 = __builtin_amdgcn_mfma_f32_32x32x16_bf16(kf[c & 1][2 * i + 1], qr[2 * c + i], p1, 0, 0, 0);
;                 }
;                 __builtin_amdgcn_sched_barrier(0);
;             }
;     ...
;             f32x2 rs2 = {0.f, 0.f};
; #pragma unroll
;             for (int r = 0; r < 16; ++r) { p0[r] = __builtin_amdgcn_exp2f(p0[r]); p1[r] = __builtin_amdgcn_exp2f(p1[r]); }
; #pragma unroll
;             for (int r = 0; r < 16; r += 2) { rs2 += (f32x2){p0[r], p0[r + 1]}; rs2 += (f32x2){p1[r], p1[r + 1]}; }
;             l += rs2.x + rs2.y;
;             bf16x8 pf[4];
;             pf[0] = pack_bf16x8(p0, 0); pf[1] = pack_bf16x8(p0, 8); pf[2] = pack_bf16x8(p1, 0); pf[3] = pack_bf16x8(p1, 8);
;             __builtin_amdgcn_sched_barrier(0);
; #pragma unroll
;             for (int d = 0; d < NDB; ++d) {
;                 if (d + 1 < NDB) {
; #pragma unroll
;                     for (int ks = 0; ks < 4; ++ks) vf[(d + 1) & 1][ks] = *(const LAS bf16x8*)(vb + (d + 1) * 32 * VROW + ks * 32);
;                 }
; #pragma unroll
;                 for (int ks = 0; ks < 4; ++ks) o[d] = __builtin_amdgcn_mfma_f32_32x32x16_bf16(vf[d & 1][ks], pf[ks], o[d], 0, 0, 0);
;                 __builtin_amdgcn_sched_barrier(0);
;             }
.Lr_top1:
	s_cmp_eq_u32 s3, 0
	s_cbranch_scc1 .Lr_gen1
	s_add_i32 s13, s3, 1
	s_cmp_ge_i32 s13, s20
	s_cbranch_scc1 .Lr_gen1
	s_add_i32 s12, s3, 1
	s_and_b32 s12, s12, 3
	s_mulk_i32 s12, 0x5800
	v_add_u32_e32 v206, s12, v246
	ds_read_b128 v[96:99], v206 offset:0
	ds_read_b128 v[100:103], v206 offset:832
	ds_read_b128 v[104:107], v206 offset:6656
	ds_read_b128 v[108:111], v206 offset:7488
	ds_read_b128 v[112:115], v206 offset:64
	ds_read_b128 v[116:119], v206 offset:896
	ds_read_b128 v[120:123], v206 offset:6720
	ds_read_b128 v[124:127], v206 offset:7552
	s_and_b32 s16, s3, 3
	s_mulk_i32 s16, 0x5800
	v_add_u32_e32 v207, s16, v247
	v_mfma_f32_16x16x32_bf16 v[32:35], v[152:155], v[64:67], v[32:35]
	v_mfma_f32_16x16x32_bf16 v[16:19], v[152:155], v[80:83], v[16:19]
	v_exp_f32_e32 v214, v214
	v_exp_f32_e32 v215, v215
	v_mfma_f32_16x16x32_bf16 v[36:39], v[156:159], v[64:67], v[36:39]
	v_mfma_f32_16x16x32_bf16 v[20:23], v[156:159], v[80:83], v[20:23]
	v_exp_f32_e32 v230, v230
	v_exp_f32_e32 v231, v231
	v_pk_add_f32 v[204:205], v[214:215], 0 op_sel_hi:[1,0]
	v_mfma_f32_16x16x32_bf16 v[40:43], v[160:163], v[64:67], v[40:43]
	v_mfma_f32_16x16x32_bf16 v[24:27], v[160:163], v[80:83], v[24:27]
	v_exp_f32_e32 v216, v216
	v_exp_f32_e32 v217, v217
	v_pk_add_f32 v[208:209], v[230:231], 0 op_sel_hi:[1,0]
	v_mfma_f32_16x16x32_bf16 v[44:47], v[164:167], v[64:67], v[44:47]
	v_mfma_f32_16x16x32_bf16 v[28:31], v[164:167], v[80:83], v[28:31]
	v_exp_f32_e32 v232, v232
	v_exp_f32_e32 v233, v233
	v_pk_add_f32 v[204:205], v[216:217], v[204:205]
	ds_read_b128 v[152:155], v207 offset:13312
	ds_read_b128 v[156:159], v207 offset:15616
	ds_read_b128 v[160:163], v207 offset:17920
	ds_read_b128 v[164:167], v207 offset:20224
	v_mfma_f32_16x16x32_bf16 v[32:35], v[188:191], v[68:71], v[32:35]
	v_mfma_f32_16x16x32_bf16 v[16:19], v[188:191], v[84:87], v[16:19]
	v_exp_f32_e32 v218, v218
	v_exp_f32_e32 v219, v219
	v_pk_add_f32 v[208:209], v[232:233], v[208:209]
	v_mfma_f32_16x16x32_bf16 v[36:39], v[192:195], v[68:71], v[36:39]
	v_mfma_f32_16x16x32_bf16 v[20:23], v[192:195], v[84:87], v[20:23]
	v_exp_f32_e32 v234, v234
	v_exp_f32_e32 v235, v235
	v_pk_add_f32 v[204:205], v[218:219], v[204:205]
	v_mfma_f32_16x16x32_bf16 v[40:43], v[196:199], v[68:71], v[40:43]
	v_mfma_f32_16x16x32_bf16 v[24:27], v[196:199], v[84:87], v[24:27]
	v_exp_f32_e32 v220, v220
	v_exp_f32_e32 v221, v221
	v_pk_add_f32 v[208:209], v[234:235], v[208:209]
	v_mfma_f32_16x16x32_bf16 v[44:47], v[200:203], v[68:71], v[44:47]
	v_mfma_f32_16x16x32_bf16 v[28:31], v[200:203], v[84:87], v[28:31]
	v_exp_f32_e32 v236, v236
	v_exp_f32_e32 v237, v237
	v_pk_add_f32 v[204:205], v[220:221], v[204:205]
	s_waitcnt lgkmcnt(8)
	v_mfma_f32_16x16x32_bf16 v[64:67], v[96:99], v[2:5], v[48:51]
	v_mfma_f32_16x16x32_bf16 v[80:83], v[96:99], v[128:131], v[52:55]
	v_exp_f32_e32 v222, v222
	v_exp_f32_e32 v223, v223
	v_pk_add_f32 v[208:209], v[236:237], v[208:209]
	v_mfma_f32_16x16x32_bf16 v[68:71], v[100:103], v[2:5], v[48:51]
	v_mfma_f32_16x16x32_bf16 v[84:87], v[100:103], v[128:131], v[52:55]
	v_exp_f32_e32 v238, v238
	v_exp_f32_e32 v239, v239
	v_pk_add_f32 v[204:205], v[222:223], v[204:205]
	v_mfma_f32_16x16x32_bf16 v[72:75], v[104:107], v[2:5], v[48:51]
	v_mfma_f32_16x16x32_bf16 v[88:91], v[104:107], v[128:131], v[52:55]
	v_exp_f32_e32 v224, v224
	v_exp_f32_e32 v225, v225
	v_pk_add_f32 v[208:209], v[238:239], v[208:209]
	v_mfma_f32_16x16x32_bf16 v[76:79], v[108:111], v[2:5], v[48:51]
	v_mfma_f32_16x16x32_bf16 v[92:95], v[108:111], v[128:131], v[52:55]
	v_exp_f32_e32 v240, v240
	v_exp_f32_e32 v241, v241
	v_pk_add_f32 v[204:205], v[224:225], v[204:205]
	ds_read_b128 v[96:99], v206 offset:128
	ds_read_b128 v[100:103], v206 offset:960
	ds_read_b128 v[104:107], v206 offset:6784
	ds_read_b128 v[108:111], v206 offset:7616
	s_waitcnt lgkmcnt(8)
	v_mfma_f32_16x16x32_bf16 v[64:67], v[112:115], v[6:9], v[64:67]
	v_mfma_f32_16x16x32_bf16 v[80:83], v[112:115], v[132:135], v[80:83]
	v_exp_f32_e32 v226, v226
	v_exp_f32_e32 v227, v227
	v_pk_add_f32 v[208:209], v[240:241], v[208:209]
	v_mfma_f32_16x16x32_bf16 v[68:71], v[116:119], v[6:9], v[68:71]
	v_mfma_f32_16x16x32_bf16 v[84:87], v[116:119], v[132:135], v[84:87]
	v_exp_f32_e32 v242, v242
	v_exp_f32_e32 v243, v243
	v_pk_add_f32 v[204:205], v[226:227], v[204:205]
	v_mfma_f32_16x16x32_bf16 v[72:75], v[120:123], v[6:9], v[72:75]
	v_mfma_f32_16x16x32_bf16 v[88:91], v[120:123], v[132:135], v[88:91]
	v_exp_f32_e32 v228, v228
	v_exp_f32_e32 v229, v229
	v_pk_add_f32 v[208:209], v[242:243], v[208:209]
	v_mfma_f32_16x16x32_bf16 v[76:79], v[124:127], v[6:9], v[76:79]
	v_mfma_f32_16x16x32_bf16 v[92:95], v[124:127], v[132:135], v[92:95]
	v_exp_f32_e32 v244, v244
	v_exp_f32_e32 v245, v245
	v_pk_add_f32 v[204:205], v[228:229], v[204:205]
	ds_read_b128 v[188:191], v207 offset:13376
	ds_read_b128 v[192:195], v207 offset:15680
	ds_read_b128 v[196:199], v207 offset:17984
	ds_read_b128 v[200:203], v207 offset:20288
	s_waitcnt lgkmcnt(4)
	v_mfma_f32_16x16x32_bf16 v[64:67], v[96:99], v[10:13], v[64:67]
	v_mfma_f32_16x16x32_bf16 v[80:83], v[96:99], v[136:139], v[80:83]
	s_nop 0
	v_pk_add_f32 v[208:209], v[244:245], v[208:209]
	v_cvt_pk_bf16_f32 v214, v214, v215
	v_cvt_pk_bf16_f32 v215, v216, v217
	v_cvt_pk_bf16_f32 v216, v218, v219
	v_cvt_pk_bf16_f32 v217, v220, v221
	v_mfma_f32_16x16x32_bf16 v[68:71], v[100:103], v[10:13], v[68:71]
	v_mfma_f32_16x16x32_bf16 v[84:87], v[100:103], v[136:139], v[84:87]
	v_cvt_pk_bf16_f32 v218, v222, v223
	v_cvt_pk_bf16_f32 v219, v224, v225
	v_cvt_pk_bf16_f32 v220, v226, v227
	v_cvt_pk_bf16_f32 v221, v228, v229
	v_cvt_pk_bf16_f32 v230, v230, v231
	v_cvt_pk_bf16_f32 v231, v232, v233
	v_mfma_f32_16x16x32_bf16 v[72:75], v[104:107], v[10:13], v[72:75]
	v_mfma_f32_16x16x32_bf16 v[88:91], v[104:107], v[136:139], v[88:91]
	v_cvt_pk_bf16_f32 v232, v234, v235
	v_cvt_pk_bf16_f32 v233, v236, v237
	v_cvt_pk_bf16_f32 v234, v238, v239
	v_cvt_pk_bf16_f32 v235, v240, v241
	v_cvt_pk_bf16_f32 v236, v242, v243
	v_cvt_pk_bf16_f32 v237, v244, v245
	v_mfma_f32_16x16x32_bf16 v[76:79], v[108:111], v[10:13], v[76:79]
	v_mfma_f32_16x16x32_bf16 v[92:95], v[108:111], v[136:139], v[92:95]
	v_add_f32_e32 v210, v204, v205
	v_add_f32_e32 v211, v208, v209
	v_add_f32_e32 v175, v175, v210
	v_add_f32_e32 v249, v249, v211
	s_branch .Lr_tail1

; #define LAS __attribute__((address_space(3)))
; template <int DQK, int DV, int FLAGS, int qp, int kp, int vts, int op> ...
;     ...
;             bf16x8 vf[2][4];
; #pragma unroll
;             for (int ks = 0; ks < 4; ++ks) vf[0][ks] = *(const LAS bf16x8*)(vb + ks * 32);
;             __builtin_amdgcn_sched_barrier(0);
;             bool need_mask = false;
;             if (FLAGS & AF_CAUSAL) need_mask = need_mask || (kv0 + 63 > qmin_w);
;             if (FLAGS & AF_WINDOW) need_mask = need_mask || (kv0 < qmax_w - (SWA_W - 1));
;             if (need_mask) {
; #pragma unroll
;                 for (int r = 0; r < 16; ++r) { const int c = 16 * (r >> 3) + (r & 7);
;                     bool m0 = false, m1 = false;
;                     if (FLAGS & AF_CAUSAL) { m0 = m0 || (c > nrel); m1 = m1 || (c + 32 > nrel); }
;                     if (FLAGS & AF_WINDOW) { m0 = m0 || (c <= nrel - SWA_W); m1 = m1 || (c + 32 <= nrel - SWA_W); }
;                     if (m0) p0[r] = -INFINITY; if (m1) p1[r] = -INFINITY; }
;             }
;     ...
;             __builtin_amdgcn_sched_barrier(0);
; #pragma unroll
;             for (int d = 0; d < NDB; ++d) {
;                 if (d + 1 < NDB) {
; #pragma unroll
;                     for (int ks = 0; ks < 4; ++ks) vf[(d + 1) & 1][ks] = *(const LAS bf16x8*)(vb + (d + 1) * 32 * VROW + ks * 32);
;                 }
; #pragma unroll
;                 for (int ks = 0; ks < 4; ++ks) o[d] = __builtin_amdgcn_mfma_f32_32x32x16_bf16(vf[d & 1][ks], pf[ks], o[d], 0, 0, 0);
;                 __builtin_amdgcn_sched_barrier(0);
;             }
.Lr_nokr_p1:
	s_cmp_eq_u32 s3, 0
	s_cbranch_scc1 .Lr_nopv_p1
	s_cmp_gt_i32 s3, s20
	s_cbranch_scc1 .Lr_nopv_p1
	s_waitcnt lgkmcnt(8)
	v_mfma_f32_16x16x32_bf16 v[32:35], v[152:155], v[64:67], v[32:35]
	v_mfma_f32_16x16x32_bf16 v[16:19], v[152:155], v[80:83], v[16:19]
	v_mfma_f32_16x16x32_bf16 v[36:39], v[156:159], v[64:67], v[36:39]
	v_mfma_f32_16x16x32_bf16 v[20:23], v[156:159], v[80:83], v[20:23]
	v_mfma_f32_16x16x32_bf16 v[40:43], v[160:163], v[64:67], v[40:43]
	v_mfma_f32_16x16x32_bf16 v[24:27], v[160:163], v[80:83], v[24:27]
	v_mfma_f32_16x16x32_bf16 v[44:47], v[164:167], v[64:67], v[44:47]
	v_mfma_f32_16x16x32_bf16 v[28:31], v[164:167], v[80:83], v[28:31]
	v_mfma_f32_16x16x32_bf16 v[32:35], v[188:191], v[68:71], v[32:35]
	v_mfma_f32_16x16x32_bf16 v[16:19], v[188:191], v[84:87], v[16:19]
	v_mfma_f32_16x16x32_bf16 v[36:39], v[192:195], v[68:71], v[36:39]
	v_mfma_f32_16x16x32_bf16 v[20:23], v[192:195], v[84:87], v[20:23]
	v_mfma_f32_16x16x32_bf16 v[40:43], v[196:199], v[68:71], v[40:43]
	v_mfma_f32_16x16x32_bf16 v[24:27], v[196:199], v[84:87], v[24:27]
	v_mfma_f32_16x16x32_bf16 v[44:47], v[200:203], v[68:71], v[44:47]
	v_mfma_f32_16x16x32_bf16 v[28:31], v[200:203], v[84:87], v[28:31]
.Lr_nopv_p1:
	s_cmp_ge_i32 s3, s20
	s_cbranch_scc1 .Lr_nosm_p1
	s_and_b32 s16, s3, 3
	s_mulk_i32 s16, 0x5800
	v_add_u32_e32 v207, s16, v247
	ds_read_b128 v[152:155], v207 offset:13312
	ds_read_b128 v[156:159], v207 offset:15616
	ds_read_b128 v[160:163], v207 offset:17920
	ds_read_b128 v[164:167], v207 offset:20224
	ds_read_b128 v[188:191], v207 offset:13376
	ds_read_b128 v[192:195], v207 offset:15680
	ds_read_b128 v[196:199], v207 offset:17984
	ds_read_b128 v[200:203], v207 offset:20288
	s_nop 7
	s_nop 7
	s_add_i32 s12, s3, 1
	s_cmp_lg_u32 s12, s20
	s_cbranch_scc1 .Lr_nomask_p1
	s_lshl_b32 s12, s3, 6
	v_subrev_u32_e32 v210, s12, v248
	v_add_u32_e32 v211, 16, v210
	v_cmp_gt_i32_e64 s[40:41], 0, v210
	v_cmp_gt_i32_e64 s[42:43], 1, v210
	v_cmp_gt_i32_e64 s[44:45], 2, v210
	v_cmp_gt_i32_e64 s[46:47], 3, v210
	v_cndmask_b32_e64 v214, v214, v182, s[40:41]
	v_cmp_gt_i32_e64 s[40:41], 4, v210
	v_cndmask_b32_e64 v215, v215, v182, s[42:43]
	v_cmp_gt_i32_e64 s[42:43], 5, v210
	v_cndmask_b32_e64 v216, v216, v182, s[44:45]
	v_cmp_gt_i32_e64 s[44:45], 6, v210
	v_cndmask_b32_e64 v217, v217, v182, s[46:47]
	v_cmp_gt_i32_e64 s[46:47], 7, v210
	v_cndmask_b32_e64 v218, v218, v182, s[40:41]
	v_cmp_gt_i32_e64 s[40:41], 32, v210
	v_cndmask_b32_e64 v219, v219, v182, s[42:43]
	v_cmp_gt_i32_e64 s[42:43], 33, v210
	v_cndmask_b32_e64 v220, v220, v182, s[44:45]
	v_cmp_gt_i32_e64 s[44:45], 34, v210
	v_cndmask_b32_e64 v221, v221, v182, s[46:47]
	v_cmp_gt_i32_e64 s[46:47], 35, v210
	v_cndmask_b32_e64 v222, v222, v182, s[40:41]
	v_cmp_gt_i32_e64 s[40:41], 36, v210
	v_cndmask_b32_e64 v223, v223, v182, s[42:43]
	v_cmp_gt_i32_e64 s[42:43], 37, v210
	v_cndmask_b32_e64 v224, v224, v182, s[44:45]
	v_cmp_gt_i32_e64 s[44:45], 38, v210
	v_cndmask_b32_e64 v225, v225, v182, s[46:47]
	v_cmp_gt_i32_e64 s[46:47], 39, v210
	v_cndmask_b32_e64 v226, v226, v182, s[40:41]
	v_cmp_gt_i32_e64 s[40:41], 0, v211
	v_cndmask_b32_e64 v227, v227, v182, s[42:43]
	v_cmp_gt_i32_e64 s[42:43], 1, v211
	v_cndmask_b32_e64 v228, v228, v182, s[44:45]
	v_cmp_gt_i32_e64 s[44:45], 2, v211
	v_cndmask_b32_e64 v229, v229, v182, s[46:47]
	v_cmp_gt_i32_e64 s[46:47], 3, v211
	v_cndmask_b32_e64 v230, v230, v182, s[40:41]
	v_cmp_gt_i32_e64 s[40:41], 4, v211
	v_cndmask_b32_e64 v231, v231, v182, s[42:43]
	v_cmp_gt_i32_e64 s[42:43], 5, v211
	v_cndmask_b32_e64 v232, v232, v182, s[44:45]
	v_cmp_gt_i32_e64 s[44:45], 6, v211
	v_cndmask_b32_e64 v233, v233, v182, s[46:47]
	v_cmp_gt_i32_e64 s[46:47], 7, v211
	v_cndmask_b32_e64 v234, v234, v182, s[40:41]
	v_cmp_gt_i32_e64 s[40:41], 32, v211
	v_cndmask_b32_e64 v235, v235, v182, s[42:43]
	v_cmp_gt_i32_e64 s[42:43], 33, v211
	v_cndmask_b32_e64 v236, v236, v182, s[44:45]
	v_cmp_gt_i32_e64 s[44:45], 34, v211
	v_cndmask_b32_e64 v237, v237, v182, s[46:47]
	v_cmp_gt_i32_e64 s[46:47], 35, v211
	v_cndmask_b32_e64 v238, v238, v182, s[40:41]
	v_cmp_gt_i32_e64 s[40:41], 36, v211
	v_cndmask_b32_e64 v239, v239, v182, s[42:43]
	v_cmp_gt_i32_e64 s[42:43], 37, v211
	v_cndmask_b32_e64 v240, v240, v182, s[44:45]
	v_cmp_gt_i32_e64 s[44:45], 38, v211
	v_cndmask_b32_e64 v241, v241, v182, s[46:47]
	v_cmp_gt_i32_e64 s[46:47], 39, v211
	v_cndmask_b32_e64 v242, v242, v182, s[40:41]
	v_cndmask_b32_e64 v243, v243, v182, s[42:43]
	v_cndmask_b32_e64 v244, v244, v182, s[44:45]
	v_cndmask_b32_e64 v245, v245, v182, s[46:47]
; #define MX3(a, b, c) __builtin_fmaxf(__builtin_fmaxf((a), (b)), (c))
; template <int DQK, int DV, int FLAGS, int qp, int kp, int vts, int op> ...
;     ...
;             float mx = 0.f;
;             if ((FLAGS & AF_ROBUST) || !started || !skipmax) {
;               float a = MX3(p0[0], p0[1], p1[0]), b = MX3(p0[2], p0[3], p1[1]); a = MX3(a, p1[2], p1[3]);
; #pragma unroll
;               for (int r = 4; r < 16; r += 4) { a = MX3(a, p0[r], p0[r + 1]); b = MX3(b, p0[r + 2], p0[r + 3]); a = MX3(a, p1[r], p1[r + 1]); b = MX3(b, p1[r + 2], p1[r + 3]); }
;               mx = __builtin_fmaxf(a, b);
;               if ((FLAGS & AF_ROBUST) || !started) mx = __builtin_fmaxf(mx, shfl_xor_l(mx, 32, lane)); }
;             if (FLAGS & AF_ROBUST) {
;                 if (__any(mx > m + 8.0f)) {
;                     const float mn = fmaxf(m, mx), alpha = __builtin_amdgcn_exp2f(m - mn);
;                     l *= alpha; m = mn;
; #pragma unroll
;                     for (int d = 0; d < NDB; ++d)
; #pragma unroll
;                         for (int r = 0; r < 16; ++r) o[d][r] *= alpha;
;                 }
; #pragma unroll
;                 for (int r = 0; r < 16; ++r) { p0[r] -= m; p1[r] -= m; }
;             } else {
;                 if (!started) {
;                     started = true;
;                     m = mx;
; #pragma unroll
;                     for (int r = 0; r < 16; ++r) { p0[r] -= mx; p1[r] -= mx; }
;                     if (!(FLAGS & AF_ALIBI)) {
; #pragma unroll
;                         for (int r = 0; r < 16; ++r) negm[r] = -m;
;                     }
;                 } else if (!skipmax && __any(mx > 64.0f)) {
;                     mx = __builtin_fmaxf(mx, shfl_xor_l(mx, 32, lane));
;                     const float dl = __builtin_fmaxf(mx, 0.f), alpha = __builtin_amdgcn_exp2f(-dl);
;                     m += dl; l *= alpha;
; #pragma unroll
;                     for (int r = 0; r < 16; ++r) { p0[r] -= dl; p1[r] -= dl; }
; #pragma unroll
;                     for (int d = 0; d < NDB; ++d)
; #pragma unroll
;                         for (int r = 0; r < 16; ++r) o[d][r] *= alpha;
;                     if (!(FLAGS & AF_ALIBI)) {
; #pragma unroll
;                         for (int r = 0; r < 16; ++r) negm[r] = -m;
;                     }
;                 }
;             }
;             f32x2 rs2 = {0.f, 0.f};
; #pragma unroll
.Lr_nomask_p1:
	s_cmp_lg_u32 s3, 0
	s_cbranch_scc1 .Lr_notfirst_p1
	v_max3_f32 v59, v214, v215, v216
	v_max3_f32 v60, v230, v231, v232
	v_max3_f32 v59, v59, v217, v218
	v_max3_f32 v60, v60, v233, v234
	v_max3_f32 v59, v59, v219, v220
	v_max3_f32 v60, v60, v235, v236
	v_max3_f32 v59, v59, v221, v222
	v_max3_f32 v60, v60, v237, v238
	v_max3_f32 v59, v59, v223, v224
	v_max3_f32 v60, v60, v239, v240
	v_max3_f32 v59, v59, v225, v226
	v_max3_f32 v60, v60, v241, v242
	v_max3_f32 v59, v59, v227, v228
	v_max3_f32 v60, v60, v243, v244
	v_max_f32_e32 v59, v59, v229
	v_max_f32_e32 v60, v60, v245
	s_nop 1
	ds_bpermute_b32 v61, v251, v59
	ds_bpermute_b32 v62, v251, v60
	s_waitcnt lgkmcnt(0)
	v_max_f32_e32 v59, v59, v61
	v_max_f32_e32 v60, v60, v62
	s_nop 1
	ds_bpermute_b32 v61, v15, v59
	ds_bpermute_b32 v62, v15, v60
	s_waitcnt lgkmcnt(0)
	v_max_f32_e32 v183, v59, v61
	v_max_f32_e32 v250, v60, v62
	v_sub_f32_e32 v214, v214, v183
	v_sub_f32_e32 v230, v230, v250
	v_sub_f32_e32 v215, v215, v183
	v_sub_f32_e32 v231, v231, v250
	v_sub_f32_e32 v216, v216, v183
	v_sub_f32_e32 v232, v232, v250
	v_sub_f32_e32 v217, v217, v183
	v_sub_f32_e32 v233, v233, v250
	v_sub_f32_e32 v218, v218, v183
	v_sub_f32_e32 v234, v234, v250
	v_sub_f32_e32 v219, v219, v183
	v_sub_f32_e32 v235, v235, v250
	v_sub_f32_e32 v220, v220, v183
	v_sub_f32_e32 v236, v236, v250
	v_sub_f32_e32 v221, v221, v183
	v_sub_f32_e32 v237, v237, v250
	v_sub_f32_e32 v222, v222, v183
	v_sub_f32_e32 v238, v238, v250
	v_sub_f32_e32 v223, v223, v183
	v_sub_f32_e32 v239, v239, v250
	v_sub_f32_e32 v224, v224, v183
	v_sub_f32_e32 v240, v240, v250
	v_sub_f32_e32 v225, v225, v183
	v_sub_f32_e32 v241, v241, v250
	v_sub_f32_e32 v226, v226, v183
	v_sub_f32_e32 v242, v242, v250
	v_sub_f32_e32 v227, v227, v183
	v_sub_f32_e32 v243, v243, v250
	v_sub_f32_e32 v228, v228, v183
	v_sub_f32_e32 v244, v244, v250
	v_sub_f32_e32 v229, v229, v183
	v_sub_f32_e32 v245, v245, v250
	v_xor_b32_e32 v48, 0x80000000, v183
	v_xor_b32_e32 v52, 0x80000000, v250
	v_mov_b32_e32 v49, v48
	v_mov_b32_e32 v53, v52
	v_mov_b32_e32 v50, v48
	v_mov_b32_e32 v54, v52
	v_mov_b32_e32 v51, v48
	v_mov_b32_e32 v55, v52
.Lr_notfirst_p1:
	v_exp_f32_e32 v214, v214
	v_exp_f32_e32 v215, v215
	v_exp_f32_e32 v230, v230
	v_exp_f32_e32 v231, v231
	v_pk_add_f32 v[204:205], v[214:215], 0 op_sel_hi:[1,0]
	v_exp_f32_e32 v216, v216
	v_exp_f32_e32 v217, v217
	v_pk_add_f32 v[208:209], v[230:231], 0 op_sel_hi:[1,0]
	v_exp_f32_e32 v232, v232
	v_exp_f32_e32 v233, v233
	v_pk_add_f32 v[204:205], v[216:217], v[204:205]
	v_exp_f32_e32 v218, v218
	v_exp_f32_e32 v219, v219
	v_pk_add_f32 v[208:209], v[232:233], v[208:209]
	v_exp_f32_e32 v234, v234
	v_exp_f32_e32 v235, v235
	v_pk_add_f32 v[204:205], v[218:219], v[204:205]
	v_exp_f32_e32 v220, v220
	v_exp_f32_e32 v221, v221
	v_pk_add_f32 v[208:209], v[234:235], v[208:209]
	v_exp_f32_e32 v236, v236
	v_exp_f32_e32 v237, v237
	v_pk_add_f32 v[204:205], v[220:221], v[204:205]
	v_exp_f32_e32 v222, v222
	v_exp_f32_e32 v223, v223
	v_pk_add_f32 v[208:209], v[236:237], v[208:209]
	v_exp_f32_e32 v238, v238
	v_exp_f32_e32 v239, v239
	v_pk_add_f32 v[204:205], v[222:223], v[204:205]
	v_exp_f32_e32 v224, v224
	v_exp_f32_e32 v225, v225
	v_pk_add_f32 v[208:209], v[238:239], v[208:209]
	v_exp_f32_e32 v240, v240
	v_exp_f32_e32 v241, v241
	v_pk_add_f32 v[204:205], v[224:225], v[204:205]
	v_exp_f32_e32 v226, v226
	v_exp_f32_e32 v227, v227
	v_pk_add_f32 v[208:209], v[240:241], v[208:209]
	v_exp_f32_e32 v242, v242
	v_exp_f32_e32 v243, v243
	v_pk_add_f32 v[204:205], v[226:227], v[204:205]
	v_exp_f32_e32 v228, v228
	v_exp_f32_e32 v229, v229
	v_pk_add_f32 v[208:209], v[242:243], v[208:209]
	v_exp_f32_e32 v244, v244
	v_exp_f32_e32 v245, v245
	v_pk_add_f32 v[204:205], v[228:229], v[204:205]
	s_nop 0
	v_pk_add_f32 v[208:209], v[244:245], v[208:209]
	v_cvt_pk_bf16_f32 v214, v214, v215
	v_cvt_pk_bf16_f32 v215, v216, v217
	v_cvt_pk_bf16_f32 v216, v218, v219
	v_cvt_pk_bf16_f32 v217, v220, v221
	v_cvt_pk_bf16_f32 v218, v222, v223
	v_cvt_pk_bf16_f32 v219, v224, v225
	v_cvt_pk_bf16_f32 v220, v226, v227
	v_cvt_pk_bf16_f32 v221, v228, v229
	v_cvt_pk_bf16_f32 v230, v230, v231
	v_cvt_pk_bf16_f32 v231, v232, v233
	v_cvt_pk_bf16_f32 v232, v234, v235
	v_cvt_pk_bf16_f32 v233, v236, v237
	v_cvt_pk_bf16_f32 v234, v238, v239
	v_cvt_pk_bf16_f32 v235, v240, v241
	v_cvt_pk_bf16_f32 v236, v242, v243
	v_cvt_pk_bf16_f32 v237, v244, v245
	v_add_f32_e32 v210, v204, v205
	v_add_f32_e32 v211, v208, v209
	v_add_f32_e32 v175, v175, v210
	v_add_f32_e32 v249, v249, v211
.Lr_nosm_p1:
	s_cmp_ge_i32 s13, s20
	s_cbranch_scc1 .Lr_noqk_p1
	s_waitcnt lgkmcnt(0)
	v_mfma_f32_16x16x32_bf16 v[64:67], v[96:99], v[2:5], v[48:51]
	v_mfma_f32_16x16x32_bf16 v[80:83], v[96:99], v[128:131], v[52:55]
	v_mfma_f32_16x16x32_bf16 v[68:71], v[100:103], v[2:5], v[48:51]
	v_mfma_f32_16x16x32_bf16 v[84:87], v[100:103], v[128:131], v[52:55]
	v_mfma_f32_16x16x32_bf16 v[72:75], v[104:107], v[2:5], v[48:51]
	v_mfma_f32_16x16x32_bf16 v[88:91], v[104:107], v[128:131], v[52:55]
	v_mfma_f32_16x16x32_bf16 v[76:79], v[108:111], v[2:5], v[48:51]
	v_mfma_f32_16x16x32_bf16 v[92:95], v[108:111], v[128:131], v[52:55]
	v_mfma_f32_16x16x32_bf16 v[64:67], v[112:115], v[6:9], v[64:67]
	v_mfma_f32_16x16x32_bf16 v[80:83], v[112:115], v[132:135], v[80:83]
	v_mfma_f32_16x16x32_bf16 v[68:71], v[116:119], v[6:9], v[68:71]
	v_mfma_f32_16x16x32_bf16 v[84:87], v[116:119], v[132:135], v[84:87]
	v_mfma_f32_16x16x32_bf16 v[72:75], v[120:123], v[6:9], v[72:75]
	v_mfma_f32_16x16x32_bf16 v[88:91], v[120:123], v[132:135], v[88:91]
	v_mfma_f32_16x16x32_bf16 v[76:79], v[124:127], v[6:9], v[76:79]
	v_mfma_f32_16x16x32_bf16 v[92:95], v[124:127], v[132:135], v[92:95]
	ds_read_b128 v[96:99], v206 offset:128
	ds_read_b128 v[100:103], v206 offset:960
	ds_read_b128 v[104:107], v206 offset:6784
	ds_read_b128 v[108:111], v206 offset:7616
	s_waitcnt lgkmcnt(0)
	v_mfma_f32_16x16x32_bf16 v[64:67], v[96:99], v[10:13], v[64:67]
	v_mfma_f32_16x16x32_bf16 v[80:83], v[96:99], v[136:139], v[80:83]
	v_mfma_f32_16x16x32_bf16 v[68:71], v[100:103], v[10:13], v[68:71]
	v_mfma_f32_16x16x32_bf16 v[84:87], v[100:103], v[136:139], v[84:87]
	v_mfma_f32_16x16x32_bf16 v[72:75], v[104:107], v[10:13], v[72:75]
	v_mfma_f32_16x16x32_bf16 v[88:91], v[104:107], v[136:139], v[88:91]
	v_mfma_f32_16x16x32_bf16 v[76:79], v[108:111], v[10:13], v[76:79]
	v_mfma_f32_16x16x32_bf16 v[92:95], v[108:111], v[136:139], v[92:95]

; #define LAS __attribute__((address_space(3)))
; __device__ __forceinline__ unsigned pk2(float lo, float hi) { f32x2 v = {lo, hi}; bf16x2_t b = __builtin_convertvector(v, bf16x2_t); return __builtin_bit_cast(unsigned, b); }
; __device__ __forceinline__ float shfl_xor_l(float v, int o, int lane) { return __builtin_bit_cast(float, __builtin_amdgcn_ds_bpermute((lane ^ o) << 2, __builtin_bit_cast(int, v))); }
; #define ATT_LSTORE(buf) do { LAS unsigned char* b_ = lds + (buf) * BUF; \
;         _Pragma("unroll") for (int i = 0; i < KPT; ++i) { if (KCH % NTHREADS == 0 || tid + i * NTHREADS < KCH) *(LAS u32x4*)(b_ + klo[i]) = kreg[i]; } \
;         _Pragma("unroll") for (int i = 0; i < VPT; ++i) *(LAS u32x4*)(b_ + vlo[i]) = vreg[i]; } while (0)
; template <int DQK, int DV, int FLAGS, int qp, int kp, int vts, int op> ...
;     ...
;             __builtin_amdgcn_sched_barrier(0);
; #pragma unroll
;             for (int d = 0; d < NDB; ++d) {
;                 if (d + 1 < NDB) {
; #pragma unroll
;                     for (int ks = 0; ks < 4; ++ks) vf[(d + 1) & 1][ks] = *(const LAS bf16x8*)(vb + (d + 1) * 32 * VROW + ks * 32);
;                 }
; #pragma unroll
;                 for (int ks = 0; ks < 4; ++ks) o[d] = __builtin_amdgcn_mfma_f32_32x32x16_bf16(vf[d & 1][ks], pf[ks], o[d], 0, 0, 0);
;                 __builtin_amdgcn_sched_barrier(0);
;             }
;         }
;         if (skip && more) ATT_GLOAD((FLAGS & AF_REV) ? t - 1 : t + 1);
;         if (more) ATT_LSTORE(cur ^ 1);
;         __syncthreads();
;     }
;     ...
;     float lt = l + shfl_xor_l(l, 32, lane);
;     if (FLAGS & AF_SINK) lt += __builtin_amdgcn_exp2f(sink2 - m);
;     const float inv = 1.0f / lt;
;     bf16* orow = O + (size_t)(32 * wave + r32) * op + 4 * hi;
; #pragma unroll
;     for (int d = 0; d < NDB; ++d)
; #pragma unroll
;         for (int g = 0; g < 4; ++g) {
;             u32x2 w; w.x = pk2(o[d][4 * g] * inv, o[d][4 * g + 1] * inv); w.y = pk2(o[d][4 * g + 2] * inv, o[d][4 * g + 3] * inv);
;             *(u32x2*)(orow + 32 * d + 8 * g) = w;
;         }
; __global__ void __launch_bounds__(NTHREADS, 2) mega_fwd(Args args) {
;     ...
;         for (int j = bid; j < 1024; j += G) {
.Lr_flush0:
	s_cmp_lt_i32 s20, s2
	s_cbranch_scc1 .Lr_epi
	s_waitcnt lgkmcnt(0)
	v_mfma_f32_16x16x32_bf16 v[32:35], v[152:155], v[214:217], v[32:35]
	v_mfma_f32_16x16x32_bf16 v[16:19], v[152:155], v[230:233], v[16:19]
	v_mfma_f32_16x16x32_bf16 v[36:39], v[156:159], v[214:217], v[36:39]
	v_mfma_f32_16x16x32_bf16 v[20:23], v[156:159], v[230:233], v[20:23]
	v_mfma_f32_16x16x32_bf16 v[40:43], v[160:163], v[214:217], v[40:43]
	v_mfma_f32_16x16x32_bf16 v[24:27], v[160:163], v[230:233], v[24:27]
	v_mfma_f32_16x16x32_bf16 v[44:47], v[164:167], v[214:217], v[44:47]
	v_mfma_f32_16x16x32_bf16 v[28:31], v[164:167], v[230:233], v[28:31]
	v_mfma_f32_16x16x32_bf16 v[32:35], v[188:191], v[218:221], v[32:35]
	v_mfma_f32_16x16x32_bf16 v[16:19], v[188:191], v[234:237], v[16:19]
	v_mfma_f32_16x16x32_bf16 v[36:39], v[192:195], v[218:221], v[36:39]
	v_mfma_f32_16x16x32_bf16 v[20:23], v[192:195], v[234:237], v[20:23]
	v_mfma_f32_16x16x32_bf16 v[40:43], v[196:199], v[218:221], v[40:43]
	v_mfma_f32_16x16x32_bf16 v[24:27], v[196:199], v[234:237], v[24:27]
	v_mfma_f32_16x16x32_bf16 v[44:47], v[200:203], v[218:221], v[44:47]
	v_mfma_f32_16x16x32_bf16 v[28:31], v[200:203], v[234:237], v[28:31]
	s_branch .Lr_epi
.Lr_flush1:
	s_cmp_lt_i32 s20, s2
	s_cbranch_scc1 .Lr_epi
	s_waitcnt lgkmcnt(0)
	v_mfma_f32_16x16x32_bf16 v[32:35], v[152:155], v[64:67], v[32:35]
	v_mfma_f32_16x16x32_bf16 v[16:19], v[152:155], v[80:83], v[16:19]
	v_mfma_f32_16x16x32_bf16 v[36:39], v[156:159], v[64:67], v[36:39]
	v_mfma_f32_16x16x32_bf16 v[20:23], v[156:159], v[80:83], v[20:23]
	v_mfma_f32_16x16x32_bf16 v[40:43], v[160:163], v[64:67], v[40:43]
	v_mfma_f32_16x16x32_bf16 v[24:27], v[160:163], v[80:83], v[24:27]
	v_mfma_f32_16x16x32_bf16 v[44:47], v[164:167], v[64:67], v[44:47]
	v_mfma_f32_16x16x32_bf16 v[28:31], v[164:167], v[80:83], v[28:31]
	v_mfma_f32_16x16x32_bf16 v[32:35], v[188:191], v[68:71], v[32:35]
	v_mfma_f32_16x16x32_bf16 v[16:19], v[188:191], v[84:87], v[16:19]
	v_mfma_f32_16x16x32_bf16 v[36:39], v[192:195], v[68:71], v[36:39]
	v_mfma_f32_16x16x32_bf16 v[20:23], v[192:195], v[84:87], v[20:23]
	v_mfma_f32_16x16x32_bf16 v[40:43], v[196:199], v[68:71], v[40:43]
	v_mfma_f32_16x16x32_bf16 v[24:27], v[196:199], v[84:87], v[24:27]
	v_mfma_f32_16x16x32_bf16 v[44:47], v[200:203], v[68:71], v[44:47]
	v_mfma_f32_16x16x32_bf16 v[28:31], v[200:203], v[84:87], v[28:31]
	s_branch .Lr_epi
.Lr_epi:
	s_nop 1
	ds_bpermute_b32 v59, v251, v175
	ds_bpermute_b32 v60, v251, v249
	s_waitcnt lgkmcnt(0)
	v_add_f32_e32 v175, v175, v59
	v_add_f32_e32 v249, v249, v60
	s_nop 1
	ds_bpermute_b32 v59, v15, v175
	ds_bpermute_b32 v60, v15, v249
	s_waitcnt lgkmcnt(0)
	v_add_f32_e32 v175, v175, v59
	v_add_f32_e32 v249, v249, v60
	v_rcp_f32_e32 v59, v175
	v_rcp_f32_e32 v60, v249
	s_nop 0
	v_fma_f32 v61, -v175, v59, 2.0
	v_fma_f32 v62, -v249, v60, 2.0
	v_mul_f32_e32 v59, v59, v61
	v_mul_f32_e32 v60, v60, v62
	s_lshl_b32 s2, s86, 6
	s_lshl_b64 s[8:9], s[84:85], 11
	s_add_u32 s3, s74, s8
	s_addc_u32 s10, s75, s9
	s_lshl_b32 s2, s2, 1
	s_add_u32 s2, s3, s2
	s_addc_u32 s3, s10, 0
	v_lshrrev_b32_e32 v61, 6, v212
	v_and_b32_e32 v62, 15, v212
	v_lshl_or_b32 v61, v61, 5, v62
	v_bfe_u32 v62, v212, 4, 2
	v_lshlrev_b32_e32 v61, 11, v61
	v_lshl_or_b32 v56, v62, 3, v61
	v_mov_b32_e32 v57, 0
	v_lshl_add_u64 v[56:57], s[2:3], 0, v[56:57]
	s_mov_b64 s[12:13], 0x8000
	v_lshl_add_u64 v[62:63], v[56:57], 0, s[12:13]
	v_mul_f32_e32 v32, v32, v59
	v_mul_f32_e32 v33, v33, v59
	v_mul_f32_e32 v34, v34, v59
	v_mul_f32_e32 v35, v35, v59
	v_cvt_pk_bf16_f32 v32, v32, v33
	v_cvt_pk_bf16_f32 v33, v34, v35
	global_store_dwordx2 v[56:57], v[32:33], off offset:1024
	v_mul_f32_e32 v36, v36, v59
	v_mul_f32_e32 v37, v37, v59
	v_mul_f32_e32 v38, v38, v59
	v_mul_f32_e32 v39, v39, v59
	v_cvt_pk_bf16_f32 v36, v36, v37
	v_cvt_pk_bf16_f32 v37, v38, v39
	global_store_dwordx2 v[56:57], v[36:37], off offset:1056
	v_mul_f32_e32 v40, v40, v59
	v_mul_f32_e32 v41, v41, v59
	v_mul_f32_e32 v42, v42, v59
	v_mul_f32_e32 v43, v43, v59
	v_cvt_pk_bf16_f32 v40, v40, v41
	v_cvt_pk_bf16_f32 v41, v42, v43
	global_store_dwordx2 v[56:57], v[40:41], off offset:1088
	v_mul_f32_e32 v44, v44, v59
	v_mul_f32_e32 v45, v45, v59
	v_mul_f32_e32 v46, v46, v59
	v_mul_f32_e32 v47, v47, v59
	v_cvt_pk_bf16_f32 v44, v44, v45
	v_cvt_pk_bf16_f32 v45, v46, v47
	global_store_dwordx2 v[56:57], v[44:45], off offset:1120
	v_mul_f32_e32 v16, v16, v60
	v_mul_f32_e32 v17, v17, v60
	v_mul_f32_e32 v18, v18, v60
	v_mul_f32_e32 v19, v19, v60
	v_cvt_pk_bf16_f32 v16, v16, v17
	v_cvt_pk_bf16_f32 v17, v18, v19
	global_store_dwordx2 v[62:63], v[16:17], off offset:1024
	v_mul_f32_e32 v20, v20, v60
	v_mul_f32_e32 v21, v21, v60
	v_mul_f32_e32 v22, v22, v60
	v_mul_f32_e32 v23, v23, v60
	v_cvt_pk_bf16_f32 v20, v20, v21
	v_cvt_pk_bf16_f32 v21, v22, v23
	global_store_dwordx2 v[62:63], v[20:21], off offset:1056
	v_mul_f32_e32 v24, v24, v60
	v_mul_f32_e32 v25, v25, v60
	v_mul_f32_e32 v26, v26, v60
	v_mul_f32_e32 v27, v27, v60
	v_cvt_pk_bf16_f32 v24, v24, v25
	v_cvt_pk_bf16_f32 v25, v26, v27
	global_store_dwordx2 v[62:63], v[24:25], off offset:1088
	v_mul_f32_e32 v28, v28, v60
	v_mul_f32_e32 v29, v29, v60
	v_mul_f32_e32 v30, v30, v60
	v_mul_f32_e32 v31, v31, v60
	v_cvt_pk_bf16_f32 v28, v28, v29
	v_cvt_pk_bf16_f32 v29, v30, v31
	global_store_dwordx2 v[62:63], v[28:29], off offset:1120
	s_mov_b64 s[90:91], s[0:1]
	s_mov_b32 s24, 0x2aaaaaab
	s_movk_i32 s25, 0xfad0
	v_readlane_b32 s0, v252, 18
	v_readlane_b32 s1, v252, 19
	s_nop 3
	s_load_dword s2, s[0:1], 0x0
	s_waitcnt lgkmcnt(0)
	s_add_i32 s33, s2, s33
	s_cmpk_lt_i32 s33, 0x400
	s_cbranch_scc0 .LBB0_573
	s_branch .LBB0_526
